# rowwise mid/end: 64-lane row sums by DPP adds + lane-63 broadcast instead of the six-hop ds_bpermute butterfly (no LDS round trips)
# speedup vs baseline: 1.0026x; 1.0026x over previous
; __device__ __forceinline__ void rowwise_phase(const Args& a, LAS unsigned char* lds, bool from_partials, bool has_y, bool has_h, bool xin_bf, int xout_mode, ...
;     ...
;         for (int r = wave * 4; r < 256; r += 32) {
;             float v[4][2][8]; v4u yv[4][2];
; #pragma unroll
;             for (int h = 0; h < 4; ++h)
; #pragma unroll
;                 for (int j = 0; j < 2; ++j) { const size_t off = ((size_t)tile * 256 + r + h) * DM + 8 * lane + 512 * j;
;                     if (xin_bf) unpack8(__builtin_nontemporal_load((const v4u*)((const bf16*)xin + off)), v[h][j]);
;                     else { const f32x4 p0 = __builtin_nontemporal_load((const f32x4*)((const float*)xin + off)), p1 = __builtin_nontemporal_load((const f32x4*)((const float*)xin + off + 4));
;                         v[h][j][0] = p0.x; v[h][j][1] = p0.y; v[h][j][2] = p0.z; v[h][j][3] = p0.w; v[h][j][4] = p1.x; v[h][j][5] = p1.y; v[h][j][6] = p1.z; v[h][j][7] = p1.w; }
;                     yv[h][j] = has_y ? __builtin_nontemporal_load((const v4u*)(y + off)) : (v4u){0u, 0u, 0u, 0u}; }
;             if (has_y) {
;                 float rstd[4];
; #pragma unroll
;                 for (int h = 0; h < 4; ++h) { float ss = 0.f;
; #pragma unroll
;                     for (int j = 0; j < 2; ++j) { float yf[8]; unpack8(yv[h][j], yf);
; #pragma unroll
;                         for (int e = 0; e < 8; ++e) ss += yf[e] * yf[e]; }
.LBB0_517:
	v_lshl_add_u64 v[10:11], v[4:5], 0, v[8:9]
	v_add_co_u32_e32 v28, vcc, 0x32000000, v10
	s_brev_b32 s16, 48
	s_nop 0
	v_addc_co_u32_e32 v29, vcc, 0, v11, vcc
	v_add_co_u32_e32 v30, vcc, s16, v10
	s_mov_b32 s16, 0x2a000000
	s_nop 0
	v_addc_co_u32_e32 v31, vcc, 0, v11, vcc
	v_add_co_u32_e32 v104, vcc, s68, v10
	v_add_u32_e32 v23, 32, v23
	s_nop 0
	v_addc_co_u32_e32 v105, vcc, 0, v11, vcc
	v_lshl_add_u64 v[8:9], v[8:9], 0, s[34:35]
	v_add_co_u32_e32 v232, vcc, s15, v10
	s_nop 1
	v_addc_co_u32_e32 v233, vcc, 0, v11, vcc
	global_load_dwordx4 v[200:203], v[28:29], off nt
	global_load_dwordx4 v[88:91], v[104:105], off offset:-4096 nt
	global_load_dwordx4 v[208:211], v[28:29], off offset:1024 nt
	global_load_dwordx4 v[96:99], v[30:31], off offset:1024 nt
	global_load_dwordx4 v[212:215], v[28:29], off offset:2048 nt
	global_load_dwordx4 v[100:103], v[30:31], off offset:2048 nt
	global_load_dwordx4 v[216:219], v[28:29], off offset:3072 nt
	global_load_dwordx4 v[106:109], v[30:31], off offset:3072 nt
	global_load_dwordx4 v[220:223], v[232:233], off nt
	global_load_dwordx4 v[110:113], v[104:105], off nt
	global_load_dwordx4 v[224:227], v[232:233], off offset:1024 nt
	global_load_dwordx4 v[114:117], v[104:105], off offset:1024 nt
	global_load_dwordx4 v[228:231], v[232:233], off offset:2048 nt
	global_load_dwordx4 v[118:121], v[104:105], off offset:2048 nt
	global_load_dwordx4 v[92:95], v[232:233], off offset:3072 nt
	global_load_dwordx4 v[156:159], v[104:105], off offset:3072 nt
	s_waitcnt vmcnt(15)
	v_lshlrev_b32_e32 v80, 16, v200
	v_and_b32_e32 v81, 0xffff0000, v200
	v_lshlrev_b32_e32 v82, 16, v201
	v_and_b32_e32 v83, 0xffff0000, v201
	v_lshlrev_b32_e32 v84, 16, v202
	v_and_b32_e32 v85, 0xffff0000, v202
	v_lshlrev_b32_e32 v86, 16, v203
	v_and_b32_e32 v87, 0xffff0000, v203
	s_waitcnt vmcnt(14)
	v_and_b32_e32 v130, 0xffff0000, v88
	s_waitcnt vmcnt(13)
	v_lshlrev_b32_e32 v69, 16, v208
	v_and_b32_e32 v72, 0xffff0000, v208
	v_lshlrev_b32_e32 v73, 16, v209
	v_and_b32_e32 v75, 0xffff0000, v209
	v_lshlrev_b32_e32 v76, 16, v210
	v_and_b32_e32 v77, 0xffff0000, v210
	v_lshlrev_b32_e32 v78, 16, v211
	v_and_b32_e32 v79, 0xffff0000, v211
	v_lshlrev_b32_e32 v131, 16, v88
	v_lshlrev_b32_e32 v129, 16, v89
	v_and_b32_e32 v128, 0xffff0000, v89
	v_lshlrev_b32_e32 v127, 16, v90
	v_and_b32_e32 v126, 0xffff0000, v90
	v_lshlrev_b32_e32 v125, 16, v91
	v_and_b32_e32 v124, 0xffff0000, v91
	s_waitcnt vmcnt(12)
	v_lshlrev_b32_e32 v91, 16, v98
	s_waitcnt vmcnt(11)
	v_lshlrev_b32_e32 v60, 16, v212
	v_and_b32_e32 v64, 0xffff0000, v212
	v_lshlrev_b32_e32 v65, 16, v213
	v_and_b32_e32 v67, 0xffff0000, v213
	v_lshlrev_b32_e32 v68, 16, v214
	v_and_b32_e32 v70, 0xffff0000, v214
	v_lshlrev_b32_e32 v71, 16, v215
	v_and_b32_e32 v74, 0xffff0000, v215
	v_and_b32_e32 v90, 0xffff0000, v98
	v_lshlrev_b32_e32 v89, 16, v99
	v_and_b32_e32 v88, 0xffff0000, v99
	s_waitcnt vmcnt(10)
	v_and_b32_e32 v138, 0xffff0000, v100
	s_waitcnt vmcnt(9)
	v_lshlrev_b32_e32 v48, 16, v216
	v_and_b32_e32 v52, 0xffff0000, v216
	v_lshlrev_b32_e32 v53, 16, v217
	v_and_b32_e32 v56, 0xffff0000, v217
	v_lshlrev_b32_e32 v57, 16, v218
	v_and_b32_e32 v61, 0xffff0000, v218
	v_lshlrev_b32_e32 v62, 16, v219
	v_and_b32_e32 v66, 0xffff0000, v219
	v_lshlrev_b32_e32 v139, 16, v100
	v_lshlrev_b32_e32 v137, 16, v101
	v_and_b32_e32 v136, 0xffff0000, v101
	v_lshlrev_b32_e32 v135, 16, v102
	v_and_b32_e32 v134, 0xffff0000, v102
	v_lshlrev_b32_e32 v133, 16, v103
	v_and_b32_e32 v132, 0xffff0000, v103
	s_waitcnt vmcnt(8)
	v_and_b32_e32 v103, 0xffff0000, v106
	v_lshlrev_b32_e32 v102, 16, v107
	v_and_b32_e32 v101, 0xffff0000, v107
	v_lshlrev_b32_e32 v100, 16, v108
	v_and_b32_e32 v99, 0xffff0000, v108
	v_lshlrev_b32_e32 v98, 16, v109
	s_waitcnt vmcnt(7)
	v_lshlrev_b32_e32 v45, 16, v220
	v_and_b32_e32 v49, 0xffff0000, v220
	v_lshlrev_b32_e32 v50, 16, v221
	v_and_b32_e32 v54, 0xffff0000, v221
	v_lshlrev_b32_e32 v55, 16, v222
	v_and_b32_e32 v58, 0xffff0000, v222
	v_lshlrev_b32_e32 v59, 16, v223
	v_and_b32_e32 v63, 0xffff0000, v223
	s_waitcnt vmcnt(6)
	v_and_b32_e32 v146, 0xffff0000, v110
	s_waitcnt vmcnt(5)
	v_lshlrev_b32_e32 v37, 16, v224
	v_and_b32_e32 v40, 0xffff0000, v224
	v_lshlrev_b32_e32 v41, 16, v225
	v_and_b32_e32 v43, 0xffff0000, v225
	v_lshlrev_b32_e32 v44, 16, v226
	v_and_b32_e32 v46, 0xffff0000, v226
	v_lshlrev_b32_e32 v47, 16, v227
	v_and_b32_e32 v51, 0xffff0000, v227
	v_mul_f32_e32 v104, v130, v130
	v_fmac_f32_e32 v104, v131, v131
	v_fmac_f32_e32 v104, v129, v129
	v_fmac_f32_e32 v104, v128, v128
	v_fmac_f32_e32 v104, v127, v127
	v_fmac_f32_e32 v104, v126, v126
	v_fmac_f32_e32 v104, v125, v125
	v_fmac_f32_e32 v104, v124, v124
	v_mul_f32_e32 v105, v138, v138
	v_fmac_f32_e32 v105, v139, v139
	v_fmac_f32_e32 v105, v137, v137
	v_fmac_f32_e32 v105, v136, v136
	v_fmac_f32_e32 v105, v135, v135
	v_fmac_f32_e32 v105, v134, v134
	v_fmac_f32_e32 v105, v133, v133
	v_fmac_f32_e32 v105, v132, v132
	v_lshlrev_b32_e32 v147, 16, v110
	v_mul_f32_e32 v122, v146, v146
	v_lshlrev_b32_e32 v145, 16, v111
	v_fmac_f32_e32 v122, v147, v147
	v_and_b32_e32 v144, 0xffff0000, v111
	v_fmac_f32_e32 v122, v145, v145
	v_lshlrev_b32_e32 v143, 16, v112
	v_fmac_f32_e32 v122, v144, v144
	v_and_b32_e32 v142, 0xffff0000, v112
	v_fmac_f32_e32 v122, v143, v143
	v_lshlrev_b32_e32 v141, 16, v113
	v_fmac_f32_e32 v122, v142, v142
	v_and_b32_e32 v140, 0xffff0000, v113
	v_fmac_f32_e32 v122, v141, v141
	v_fmac_f32_e32 v122, v140, v140
	s_waitcnt vmcnt(4)
	v_lshlrev_b32_e32 v113, 16, v114
	s_waitcnt vmcnt(3)
	v_lshlrev_b32_e32 v36, 16, v230
	s_waitcnt vmcnt(1)
; __device__ __forceinline__ void rowwise_phase(const Args& a, LAS unsigned char* lds, bool from_partials, bool has_y, bool has_h, bool xin_bf, int xout_mode, ...
;     ...
;                 for (int h = 0; h < 4; ++h) { float ss = 0.f;
; #pragma unroll
;                     for (int j = 0; j < 2; ++j) { float yf[8]; unpack8(yv[h][j], yf);
; #pragma unroll
;                         for (int e = 0; e < 8; ++e) ss += yf[e] * yf[e]; }
;                     rstd[h] = __builtin_amdgcn_rsqf(wave_sum(ss) * (1.0f / DM) + EPS); }
	v_lshlrev_b32_e32 v31, 16, v95
	v_and_b32_e32 v34, 0xffff0000, v95
	v_lshlrev_b32_e32 v95, 16, v96
	v_lshlrev_b32_e32 v28, 16, v94
	v_and_b32_e32 v30, 0xffff0000, v94
	v_and_b32_e32 v94, 0xffff0000, v96
	v_fmac_f32_e32 v104, v95, v95
	v_and_b32_e32 v38, 0xffff0000, v230
	v_lshlrev_b32_e32 v39, 16, v231
	v_and_b32_e32 v42, 0xffff0000, v231
	v_lshlrev_b32_e32 v26, 16, v93
	v_and_b32_e32 v27, 0xffff0000, v93
	v_lshlrev_b32_e32 v93, 16, v97
	v_fmac_f32_e32 v104, v94, v94
	v_lshlrev_b32_e32 v29, 16, v228
	v_and_b32_e32 v32, 0xffff0000, v228
	v_lshlrev_b32_e32 v33, 16, v229
	v_and_b32_e32 v35, 0xffff0000, v229
	v_lshlrev_b32_e32 v24, 16, v92
	v_and_b32_e32 v25, 0xffff0000, v92
	v_and_b32_e32 v92, 0xffff0000, v97
	v_fmac_f32_e32 v104, v93, v93
	v_fmac_f32_e32 v104, v92, v92
	v_fmac_f32_e32 v104, v91, v91
	v_fmac_f32_e32 v104, v90, v90
	v_fmac_f32_e32 v104, v89, v89
	v_fmac_f32_e32 v104, v88, v88
	s_nop 1
	v_add_f32_dpp v96, v104, v104 quad_perm:[1,0,3,2] row_mask:0xf bank_mask:0xf
	v_and_b32_e32 v112, 0xffff0000, v114
	v_fmac_f32_e32 v122, v113, v113
	v_lshlrev_b32_e32 v111, 16, v115
	v_fmac_f32_e32 v122, v112, v112
	s_waitcnt lgkmcnt(0)
	s_nop 1
	v_add_f32_dpp v96, v96, v96 quad_perm:[2,3,0,1] row_mask:0xf bank_mask:0xf
	s_nop 1
	v_add_f32_dpp v96, v96, v96 row_half_mirror row_mask:0xf bank_mask:0xf
	s_nop 1
	v_add_f32_dpp v96, v96, v96 row_mirror row_mask:0xf bank_mask:0xf
	s_nop 1
	v_add_f32_dpp v96, v96, v96 row_bcast:15 row_mask:0xa bank_mask:0xf
	s_nop 1
	v_add_f32_dpp v96, v96, v96 row_bcast:31 row_mask:0xc bank_mask:0xf
	s_nop 1
	v_readlane_b32 s100, v96, 63
	s_nop 1
	v_mov_b32_e32 v96, s100
	v_lshlrev_b32_e32 v104, 16, v106
	v_fmac_f32_e32 v105, v104, v104
	v_fmac_f32_e32 v105, v103, v103
	v_fmac_f32_e32 v105, v102, v102
	s_waitcnt lgkmcnt(0)
	v_fmac_f32_e32 v105, v101, v101
	v_fmac_f32_e32 v105, v100, v100
	v_fmac_f32_e32 v105, v99, v99
	v_fmac_f32_e32 v105, v98, v98
	s_waitcnt lgkmcnt(0)
	v_and_b32_e32 v110, 0xffff0000, v115
	v_fmac_f32_e32 v122, v111, v111
	v_fmac_f32_e32 v122, v110, v110
	v_and_b32_e32 v108, 0xffff0000, v116
	s_waitcnt lgkmcnt(0)
	v_lshlrev_b32_e32 v107, 16, v117
	v_and_b32_e32 v154, 0xffff0000, v118
	v_lshlrev_b32_e32 v155, 16, v118
	v_mul_f32_e32 v123, v154, v154
	s_waitcnt lgkmcnt(0)
	v_lshlrev_b32_e32 v153, 16, v119
	v_fmac_f32_e32 v123, v155, v155
	v_and_b32_e32 v152, 0xffff0000, v119
	v_fmac_f32_e32 v123, v153, v153
	s_waitcnt lgkmcnt(0)
	v_and_b32_e32 v97, 0xffff0000, v109
	v_fmac_f32_e32 v105, v97, v97
	s_nop 1
	v_add_f32_dpp v106, v105, v105 quad_perm:[1,0,3,2] row_mask:0xf bank_mask:0xf
	v_lshlrev_b32_e32 v109, 16, v116
	v_fmac_f32_e32 v122, v109, v109
	v_fmac_f32_e32 v122, v108, v108
	v_fmac_f32_e32 v122, v107, v107
	s_waitcnt lgkmcnt(0)
	s_nop 1
	v_add_f32_dpp v105, v106, v106 quad_perm:[2,3,0,1] row_mask:0xf bank_mask:0xf
	s_nop 1
	v_add_f32_dpp v105, v105, v105 row_half_mirror row_mask:0xf bank_mask:0xf
	s_nop 1
	v_add_f32_dpp v105, v105, v105 row_mirror row_mask:0xf bank_mask:0xf
	s_nop 1
	v_add_f32_dpp v105, v105, v105 row_bcast:15 row_mask:0xa bank_mask:0xf
	s_nop 1
	v_add_f32_dpp v105, v105, v105 row_bcast:31 row_mask:0xc bank_mask:0xf
	s_nop 1
	v_readlane_b32 s100, v105, 63
	s_nop 1
	v_mov_b32_e32 v105, s100
	v_lshlrev_b32_e32 v151, 16, v120
	v_fmac_f32_e32 v123, v152, v152
	v_and_b32_e32 v150, 0xffff0000, v120
	v_fmac_f32_e32 v123, v151, v151
	s_waitcnt lgkmcnt(0)
	v_lshlrev_b32_e32 v149, 16, v121
	v_fmac_f32_e32 v123, v150, v150
	v_and_b32_e32 v148, 0xffff0000, v121
	v_fmac_f32_e32 v123, v149, v149
	s_waitcnt lgkmcnt(0)
	v_fmac_f32_e32 v123, v148, v148
	s_waitcnt vmcnt(0)
	v_and_b32_e32 v121, 0xffff0000, v156
	v_lshlrev_b32_e32 v120, 16, v157
	v_and_b32_e32 v119, 0xffff0000, v157
	s_waitcnt lgkmcnt(0)
	v_lshlrev_b32_e32 v118, 16, v158
	v_lshlrev_b32_e32 v116, 16, v159
	v_fmamk_f32 v96, v96, 0x3a800000, v194
	v_rsq_f32_e32 v96, v96
	s_waitcnt lgkmcnt(0)
	v_mul_f32_e32 v124, v96, v124
	v_mul_f32_e32 v131, v96, v131
	v_mul_f32_e32 v130, v96, v130
	s_waitcnt lgkmcnt(0)
	v_and_b32_e32 v106, 0xffff0000, v117
	v_fmac_f32_e32 v122, v106, v106
	s_nop 1
	v_add_f32_dpp v114, v122, v122 quad_perm:[1,0,3,2] row_mask:0xf bank_mask:0xf
	v_and_b32_e32 v117, 0xffff0000, v158
	v_fmamk_f32 v105, v105, 0x3a800000, v194
	v_rsq_f32_e32 v105, v105
	v_mul_f32_e32 v129, v96, v129
	s_waitcnt lgkmcnt(0)
	s_nop 1
	v_add_f32_dpp v114, v114, v114 quad_perm:[2,3,0,1] row_mask:0xf bank_mask:0xf
	s_nop 1
	v_add_f32_dpp v114, v114, v114 row_half_mirror row_mask:0xf bank_mask:0xf
	s_nop 1
	v_add_f32_dpp v114, v114, v114 row_mirror row_mask:0xf bank_mask:0xf
	s_nop 1
	v_add_f32_dpp v114, v114, v114 row_bcast:15 row_mask:0xa bank_mask:0xf
	s_nop 1
	v_add_f32_dpp v114, v114, v114 row_bcast:31 row_mask:0xc bank_mask:0xf
	s_nop 1
	v_readlane_b32 s100, v114, 63
	s_nop 1
	v_mov_b32_e32 v114, s100
	v_lshlrev_b32_e32 v122, 16, v156
	v_fmac_f32_e32 v123, v122, v122
	v_fmac_f32_e32 v123, v121, v121
	v_fmac_f32_e32 v123, v120, v120
	s_waitcnt lgkmcnt(0)
	v_fmac_f32_e32 v123, v119, v119
	v_fmac_f32_e32 v123, v118, v118
	v_fmac_f32_e32 v123, v117, v117
	v_fmac_f32_e32 v123, v116, v116
	s_waitcnt lgkmcnt(0)
	v_mul_f32_e32 v128, v96, v128
	v_mul_f32_e32 v127, v96, v127
	v_mul_f32_e32 v126, v96, v126
	v_mul_f32_e32 v125, v96, v125
	s_waitcnt lgkmcnt(0)
	v_mul_f32_e32 v88, v96, v88
	v_mul_f32_e32 v95, v96, v95
	v_mul_f32_e32 v91, v96, v91
	v_mul_f32_e32 v90, v96, v90
	s_waitcnt lgkmcnt(0)
	v_mul_f32_e32 v89, v96, v89
	v_mul_f32_e32 v94, v96, v94
	v_mul_f32_e32 v93, v96, v93
	v_mul_f32_e32 v92, v96, v92
	s_waitcnt lgkmcnt(0)
; #define LAS __attribute__((address_space(3)))
; #define LAS __attribute__((address_space(3)))
; __device__ __forceinline__ v4u pack8(const float (&f)[8]) { return (v4u){pk2(f[0], f[1]), pk2(f[2], f[3]), pk2(f[4], f[5]), pk2(f[6], f[7])}; }
; __device__ __forceinline__ void rowwise_phase(const Args& a, LAS unsigned char* lds, bool from_partials, bool has_y, bool has_h, bool xin_bf, int xout_mode, ...
;     ...
;                     rstd[h] = __builtin_amdgcn_rsqf(wave_sum(ss) * (1.0f / DM) + EPS); }
; #pragma unroll
;                 for (int j = 0; j < 2; ++j) { const LAS float* gpp = vec + 8 * lane + 512 * j; const f32x4 g0 = *(const LAS f32x4*)gpp, g1 = *(const LAS f32x4*)(gpp + 4);
;                     const float gp[8] = {g0.x, g0.y, g0.z, g0.w, g1.x, g1.y, g1.z, g1.w};
; #pragma unroll
;                     for (int h = 0; h < 4; ++h) { float yf[8]; unpack8(yv[h][j], yf);
; #pragma unroll
;                         for (int e = 0; e < 8; ++e) v[h][j][e] += gp[e] * (yf[e] * rstd[h]); } }
;             }
;             if (xout_mode == 1) {
; #pragma unroll
;                 for (int h = 0; h < 4; ++h)
; #pragma unroll
;                     for (int j = 0; j < 2; ++j) { float* o = xout + ((size_t)tile * 256 + r + h) * DM + 8 * lane + 512 * j;
;                         __builtin_nontemporal_store((f32x4){v[h][j][0], v[h][j][1], v[h][j][2], v[h][j][3]}, (f32x4*)o); __builtin_nontemporal_store((f32x4){v[h][j][4], v[h][j][5], v[h][j][6], v[h][j][7]}, (f32x4*)(o + 4)); }
;             } else if (xout_mode == 2) {
; #pragma unroll
;                 for (int h = 0; h < 4; ++h)
; #pragma unroll
;                     for (int j = 0; j < 2; ++j) { const v4u w = pack8(v[h][j]);
;                         __builtin_nontemporal_store(w, (v4u*)(xoutb + ((size_t)tile * 256 + r + h) * DM + 8 * lane + 512 * j));
;                         unpack8(w, v[h][j]); }
	v_and_b32_e32 v115, 0xffff0000, v159
	v_fmac_f32_e32 v123, v115, v115
	s_nop 1
	v_add_f32_dpp v156, v123, v123 quad_perm:[1,0,3,2] row_mask:0xf bank_mask:0xf
	v_fmamk_f32 v114, v114, 0x3a800000, v194
	v_rsq_f32_e32 v114, v114
	s_waitcnt lgkmcnt(0)
	s_nop 1
	v_add_f32_dpp v123, v156, v156 quad_perm:[2,3,0,1] row_mask:0xf bank_mask:0xf
	s_nop 1
	v_add_f32_dpp v123, v123, v123 row_half_mirror row_mask:0xf bank_mask:0xf
	s_nop 1
	v_add_f32_dpp v123, v123, v123 row_mirror row_mask:0xf bank_mask:0xf
	s_nop 1
	v_add_f32_dpp v123, v123, v123 row_bcast:15 row_mask:0xa bank_mask:0xf
	s_nop 1
	v_add_f32_dpp v123, v123, v123 row_bcast:31 row_mask:0xc bank_mask:0xf
	s_nop 1
	v_readlane_b32 s100, v123, 63
	s_nop 1
	v_mov_b32_e32 v123, s100
	s_waitcnt lgkmcnt(0)
	s_waitcnt lgkmcnt(0)
	s_waitcnt lgkmcnt(0)
	s_waitcnt lgkmcnt(0)
	s_waitcnt lgkmcnt(0)
	ds_read_b128 v[156:159], v0
	ds_read_b128 v[174:177], v0 offset:16
	v_fmamk_f32 v123, v123, 0x3a800000, v194
	v_rsq_f32_e32 v123, v123
	s_waitcnt lgkmcnt(1)
	v_fmac_f32_e32 v80, v131, v156
	s_waitcnt lgkmcnt(0)
	v_fmac_f32_e32 v87, v124, v177
	v_mul_f32_e32 v124, v105, v139
	v_fmac_f32_e32 v60, v124, v156
	v_mul_f32_e32 v124, v105, v138
	v_fmac_f32_e32 v64, v124, v157
	v_mul_f32_e32 v124, v105, v137
	v_fmac_f32_e32 v65, v124, v158
	v_mul_f32_e32 v124, v105, v136
	v_fmac_f32_e32 v67, v124, v159
	v_mul_f32_e32 v124, v105, v135
	v_fmac_f32_e32 v68, v124, v174
	v_mul_f32_e32 v124, v105, v134
	v_fmac_f32_e32 v70, v124, v175
	v_mul_f32_e32 v124, v105, v133
	v_fmac_f32_e32 v71, v124, v176
	v_mul_f32_e32 v124, v105, v132
	v_fmac_f32_e32 v74, v124, v177
	v_mul_f32_e32 v124, v114, v147
	v_fmac_f32_e32 v45, v124, v156
	v_mul_f32_e32 v124, v114, v146
	v_fmac_f32_e32 v49, v124, v157
	v_mul_f32_e32 v124, v114, v145
	v_fmac_f32_e32 v50, v124, v158
	v_mul_f32_e32 v124, v114, v144
	v_fmac_f32_e32 v54, v124, v159
	v_mul_f32_e32 v124, v114, v143
	v_fmac_f32_e32 v55, v124, v174
	v_mul_f32_e32 v124, v114, v142
	v_fmac_f32_e32 v58, v124, v175
	v_mul_f32_e32 v124, v114, v141
	v_fmac_f32_e32 v59, v124, v176
	v_mul_f32_e32 v124, v114, v140
	v_fmac_f32_e32 v63, v124, v177
	v_mul_f32_e32 v124, v123, v155
	v_fmac_f32_e32 v29, v156, v124
	v_mul_f32_e32 v124, v123, v154
	v_fmac_f32_e32 v32, v157, v124
	v_mul_f32_e32 v124, v123, v153
	v_fmac_f32_e32 v33, v158, v124
	v_mul_f32_e32 v124, v123, v152
	v_fmac_f32_e32 v35, v159, v124
	v_mul_f32_e32 v124, v123, v151
	v_fmac_f32_e32 v36, v174, v124
	v_mul_f32_e32 v124, v123, v150
	v_fmac_f32_e32 v38, v175, v124
	v_mul_f32_e32 v124, v123, v149
	v_fmac_f32_e32 v39, v176, v124
	v_mul_f32_e32 v124, v123, v148
	v_fmac_f32_e32 v81, v130, v157
	v_fmac_f32_e32 v82, v129, v158
	v_fmac_f32_e32 v83, v128, v159
	v_fmac_f32_e32 v84, v127, v174
	v_fmac_f32_e32 v85, v126, v175
	v_fmac_f32_e32 v86, v125, v176
	v_fmac_f32_e32 v42, v177, v124
	ds_read_b128 v[124:127], v0 offset:2048
	ds_read_b128 v[128:131], v0 offset:2064
	v_cvt_pk_bf16_f32 v80, v80, v81
	v_cvt_pk_bf16_f32 v81, v82, v83
	v_cvt_pk_bf16_f32 v82, v84, v85
	v_add_co_u32_e32 v84, vcc, s16, v10
	s_waitcnt lgkmcnt(0)
	v_fmac_f32_e32 v79, v88, v131
	v_mul_f32_e32 v88, v105, v104
	v_fmac_f32_e32 v48, v88, v124
	v_mul_f32_e32 v88, v105, v103
	v_fmac_f32_e32 v52, v88, v125
	v_mul_f32_e32 v88, v105, v102
	v_fmac_f32_e32 v53, v88, v126
	v_mul_f32_e32 v88, v105, v101
	v_fmac_f32_e32 v56, v88, v127
	v_mul_f32_e32 v88, v105, v100
	v_fmac_f32_e32 v57, v88, v128
	v_mul_f32_e32 v88, v105, v99
	v_fmac_f32_e32 v61, v88, v129
	v_mul_f32_e32 v88, v105, v98
	v_fmac_f32_e32 v62, v88, v130
	v_mul_f32_e32 v88, v105, v97
	v_fmac_f32_e32 v66, v88, v131
	v_mul_f32_e32 v88, v114, v113
	v_fmac_f32_e32 v37, v88, v124
	v_mul_f32_e32 v88, v114, v112
	v_fmac_f32_e32 v40, v88, v125
	v_mul_f32_e32 v88, v114, v111
	v_fmac_f32_e32 v41, v88, v126
	v_mul_f32_e32 v88, v114, v110
	v_fmac_f32_e32 v43, v88, v127
	v_mul_f32_e32 v88, v114, v109
	v_fmac_f32_e32 v44, v88, v128
	v_mul_f32_e32 v88, v114, v108
	v_fmac_f32_e32 v46, v88, v129
	v_mul_f32_e32 v88, v114, v107
	v_fmac_f32_e32 v47, v88, v130
	v_mul_f32_e32 v88, v114, v106
	v_fmac_f32_e32 v51, v88, v131
	v_mul_f32_e32 v88, v123, v122
	v_fmac_f32_e32 v24, v124, v88
	v_mul_f32_e32 v88, v123, v121
	v_fmac_f32_e32 v25, v125, v88
	v_mul_f32_e32 v88, v123, v120
	v_fmac_f32_e32 v26, v126, v88
	v_mul_f32_e32 v88, v123, v119
	v_fmac_f32_e32 v27, v127, v88
	v_mul_f32_e32 v88, v123, v118
	v_fmac_f32_e32 v28, v128, v88
	v_mul_f32_e32 v88, v123, v117
	v_addc_co_u32_e32 v85, vcc, 0, v11, vcc
	v_fmac_f32_e32 v30, v129, v88
	v_mul_f32_e32 v88, v123, v116
	v_cvt_pk_bf16_f32 v83, v86, v87
	v_add_co_u32_e32 v86, vcc, s69, v10
	v_fmac_f32_e32 v69, v95, v124
	v_fmac_f32_e32 v76, v91, v128
	v_fmac_f32_e32 v77, v90, v129
	v_fmac_f32_e32 v78, v89, v130
	v_fmac_f32_e32 v31, v130, v88
	v_mul_f32_e32 v88, v123, v115
	v_addc_co_u32_e32 v87, vcc, 0, v11, vcc
	v_fmac_f32_e32 v72, v94, v125
	v_fmac_f32_e32 v73, v93, v126
	v_fmac_f32_e32 v75, v92, v127
	v_fmac_f32_e32 v34, v131, v88
	global_store_dwordx4 v[86:87], v[80:83], off offset:-4096 nt
	v_lshlrev_b32_e32 v88, 16, v80
	v_and_b32_e32 v89, 0xffff0000, v80
	v_lshlrev_b32_e32 v90, 16, v81
	v_and_b32_e32 v91, 0xffff0000, v81
	v_lshlrev_b32_e32 v92, 16, v82
	v_and_b32_e32 v93, 0xffff0000, v82
	v_lshlrev_b32_e32 v94, 16, v83
	v_and_b32_e32 v95, 0xffff0000, v83
	v_cvt_pk_bf16_f32 v80, v69, v72
	v_cvt_pk_bf16_f32 v81, v73, v75
	v_cvt_pk_bf16_f32 v82, v76, v77
	v_cvt_pk_bf16_f32 v83, v78, v79
	global_store_dwordx4 v[84:85], v[80:83], off offset:1024 nt
	v_cvt_pk_bf16_f32 v76, v60, v64
	v_cvt_pk_bf16_f32 v77, v65, v67
	v_cvt_pk_bf16_f32 v78, v68, v70
	v_cvt_pk_bf16_f32 v79, v71, v74
	global_store_dwordx4 v[84:85], v[76:79], off offset:2048 nt
; __device__ __forceinline__ v4u pack8(const float (&f)[8]) { return (v4u){pk2(f[0], f[1]), pk2(f[2], f[3]), pk2(f[4], f[5]), pk2(f[6], f[7])}; }
; __device__ __forceinline__ void rowwise_phase(const Args& a, LAS unsigned char* lds, bool from_partials, bool has_y, bool has_h, bool xin_bf, int xout_mode, ...
;     ...
;             } else if (xout_mode == 2) {
; #pragma unroll
;                 for (int h = 0; h < 4; ++h)
; #pragma unroll
;                     for (int j = 0; j < 2; ++j) { const v4u w = pack8(v[h][j]);
;                         __builtin_nontemporal_store(w, (v4u*)(xoutb + ((size_t)tile * 256 + r + h) * DM + 8 * lane + 512 * j));
;                         unpack8(w, v[h][j]); }
;             }
;             if (has_h) {
;                 float rstd[4];
; #pragma unroll
;                 for (int h = 0; h < 4; ++h) { float ss = 0.f;
; #pragma unroll
;                     for (int j = 0; j < 2; ++j)
; #pragma unroll
;                         for (int e = 0; e < 8; ++e) ss += v[h][j][e] * v[h][j][e];
;                     rstd[h] = __builtin_amdgcn_rsqf(wave_sum(ss) * (1.0f / DM) + EPS); }
	v_cvt_pk_bf16_f32 v68, v48, v52
	v_cvt_pk_bf16_f32 v69, v53, v56
	v_cvt_pk_bf16_f32 v70, v57, v61
	v_cvt_pk_bf16_f32 v71, v62, v66
	global_store_dwordx4 v[84:85], v[68:71], off offset:3072 nt
	v_cvt_pk_bf16_f32 v52, v45, v49
	v_cvt_pk_bf16_f32 v53, v50, v54
	v_cvt_pk_bf16_f32 v54, v55, v58
	v_cvt_pk_bf16_f32 v55, v59, v63
	global_store_dwordx4 v[86:87], v[52:55], off nt
	v_cvt_pk_bf16_f32 v48, v37, v40
	v_cvt_pk_bf16_f32 v49, v41, v43
	v_cvt_pk_bf16_f32 v50, v44, v46
	v_cvt_pk_bf16_f32 v51, v47, v51
	global_store_dwordx4 v[86:87], v[48:51], off offset:1024 nt
	v_cvt_pk_bf16_f32 v44, v29, v32
	v_cvt_pk_bf16_f32 v45, v33, v35
	v_cvt_pk_bf16_f32 v46, v36, v38
	v_cvt_pk_bf16_f32 v47, v39, v42
	global_store_dwordx4 v[86:87], v[44:47], off offset:2048 nt
	v_cvt_pk_bf16_f32 v24, v24, v25
	v_cvt_pk_bf16_f32 v25, v26, v27
	v_cvt_pk_bf16_f32 v26, v28, v30
	v_cvt_pk_bf16_f32 v27, v31, v34
	global_store_dwordx4 v[86:87], v[24:27], off offset:3072 nt
	v_lshlrev_b32_e32 v86, 16, v24
	v_and_b32_e32 v87, 0xffff0000, v24
	v_mul_f32_e32 v24, v89, v89
	v_fmac_f32_e32 v24, v88, v88
	v_fmac_f32_e32 v24, v90, v90
	v_fmac_f32_e32 v24, v91, v91
	v_fmac_f32_e32 v24, v92, v92
	v_fmac_f32_e32 v24, v93, v93
	v_fmac_f32_e32 v24, v94, v94
	v_lshlrev_b32_e32 v72, 16, v80
	v_fmac_f32_e32 v24, v95, v95
	v_and_b32_e32 v73, 0xffff0000, v80
	v_fmac_f32_e32 v24, v72, v72
	v_lshlrev_b32_e32 v75, 16, v81
	v_fmac_f32_e32 v24, v73, v73
	v_and_b32_e32 v80, 0xffff0000, v81
	v_fmac_f32_e32 v24, v75, v75
	v_lshlrev_b32_e32 v81, 16, v82
	v_fmac_f32_e32 v24, v80, v80
	v_and_b32_e32 v82, 0xffff0000, v82
	v_fmac_f32_e32 v24, v81, v81
	v_lshlrev_b32_e32 v96, 16, v83
	v_fmac_f32_e32 v24, v82, v82
	v_and_b32_e32 v83, 0xffff0000, v83
	v_fmac_f32_e32 v24, v96, v96
	v_fmac_f32_e32 v24, v83, v83
	v_lshlrev_b32_e32 v104, 16, v25
	v_and_b32_e32 v105, 0xffff0000, v25
	s_nop 1
	v_add_f32_dpp v25, v24, v24 quad_perm:[1,0,3,2] row_mask:0xf bank_mask:0xf
	v_and_b32_e32 v64, 0xffff0000, v76
	v_lshlrev_b32_e32 v60, 16, v76
	v_lshlrev_b32_e32 v65, 16, v77
	v_and_b32_e32 v67, 0xffff0000, v77
	s_waitcnt lgkmcnt(0)
	s_nop 1
	v_add_f32_dpp v24, v25, v25 quad_perm:[2,3,0,1] row_mask:0xf bank_mask:0xf
	s_nop 1
	v_add_f32_dpp v24, v24, v24 row_half_mirror row_mask:0xf bank_mask:0xf
	s_nop 1
	v_add_f32_dpp v24, v24, v24 row_mirror row_mask:0xf bank_mask:0xf
	s_nop 1
	v_add_f32_dpp v24, v24, v24 row_bcast:15 row_mask:0xa bank_mask:0xf
	s_nop 1
	v_add_f32_dpp v24, v24, v24 row_bcast:31 row_mask:0xc bank_mask:0xf
	s_nop 1
	v_readlane_b32 s100, v24, 63
	s_nop 1
	v_mov_b32_e32 v24, s100
	v_lshlrev_b32_e32 v74, 16, v78
	v_and_b32_e32 v76, 0xffff0000, v78
	v_lshlrev_b32_e32 v77, 16, v79
	v_and_b32_e32 v78, 0xffff0000, v79
	s_waitcnt lgkmcnt(0)
	v_lshlrev_b32_e32 v56, 16, v68
	v_and_b32_e32 v57, 0xffff0000, v68
	v_lshlrev_b32_e32 v61, 16, v69
	v_and_b32_e32 v62, 0xffff0000, v69
	s_waitcnt lgkmcnt(0)
	v_lshlrev_b32_e32 v66, 16, v70
	v_and_b32_e32 v68, 0xffff0000, v70
	v_lshlrev_b32_e32 v69, 16, v71
	v_and_b32_e32 v70, 0xffff0000, v71
	s_waitcnt lgkmcnt(0)
	v_lshlrev_b32_e32 v58, 16, v52
	v_and_b32_e32 v52, 0xffff0000, v52
	v_lshlrev_b32_e32 v59, 16, v53
	v_and_b32_e32 v53, 0xffff0000, v53
	s_waitcnt lgkmcnt(0)
	v_lshlrev_b32_e32 v63, 16, v54
	v_and_b32_e32 v54, 0xffff0000, v54
	v_lshlrev_b32_e32 v71, 16, v55
	v_and_b32_e32 v55, 0xffff0000, v55
	s_waitcnt lgkmcnt(0)
	v_fmamk_f32 v24, v24, 0x3a800000, v194
	v_rsq_f32_e32 v110, v24
	v_mul_f32_e32 v24, v64, v64
	v_fmac_f32_e32 v24, v60, v60
	v_fmac_f32_e32 v24, v65, v65
	v_fmac_f32_e32 v24, v67, v67
	v_fmac_f32_e32 v24, v74, v74
	v_fmac_f32_e32 v24, v76, v76
	v_fmac_f32_e32 v24, v77, v77
	v_fmac_f32_e32 v24, v78, v78
	v_fmac_f32_e32 v24, v56, v56
	v_fmac_f32_e32 v24, v57, v57
	v_fmac_f32_e32 v24, v61, v61
	v_fmac_f32_e32 v24, v62, v62
	v_fmac_f32_e32 v24, v66, v66
	v_fmac_f32_e32 v24, v68, v68
	v_fmac_f32_e32 v24, v69, v69
	v_fmac_f32_e32 v24, v70, v70
	s_nop 1
	v_add_f32_dpp v25, v24, v24 quad_perm:[1,0,3,2] row_mask:0xf bank_mask:0xf
	v_lshlrev_b32_e32 v79, 16, v48
	v_and_b32_e32 v48, 0xffff0000, v48
	v_lshlrev_b32_e32 v84, 16, v49
	v_and_b32_e32 v49, 0xffff0000, v49
	s_waitcnt lgkmcnt(0)
	s_nop 1
	v_add_f32_dpp v24, v25, v25 quad_perm:[2,3,0,1] row_mask:0xf bank_mask:0xf
	s_nop 1
	v_add_f32_dpp v24, v24, v24 row_half_mirror row_mask:0xf bank_mask:0xf
	s_nop 1
	v_add_f32_dpp v24, v24, v24 row_mirror row_mask:0xf bank_mask:0xf
	s_nop 1
	v_add_f32_dpp v24, v24, v24 row_bcast:15 row_mask:0xa bank_mask:0xf
	s_nop 1
	v_add_f32_dpp v24, v24, v24 row_bcast:31 row_mask:0xc bank_mask:0xf
	s_nop 1
	v_readlane_b32 s100, v24, 63
	s_nop 1
	v_mov_b32_e32 v24, s100
	v_lshlrev_b32_e32 v85, 16, v50
	v_and_b32_e32 v50, 0xffff0000, v50
	v_lshlrev_b32_e32 v97, 16, v51
	v_and_b32_e32 v51, 0xffff0000, v51
	s_waitcnt lgkmcnt(0)
	v_and_b32_e32 v99, 0xffff0000, v44
	v_lshlrev_b32_e32 v98, 16, v44
	v_lshlrev_b32_e32 v100, 16, v45
	v_and_b32_e32 v101, 0xffff0000, v45
	s_waitcnt lgkmcnt(0)
	v_lshlrev_b32_e32 v102, 16, v46
	v_and_b32_e32 v46, 0xffff0000, v46
	v_lshlrev_b32_e32 v103, 16, v47
	v_and_b32_e32 v47, 0xffff0000, v47
	s_waitcnt lgkmcnt(0)
	v_lshlrev_b32_e32 v106, 16, v26
	v_and_b32_e32 v107, 0xffff0000, v26
	v_lshlrev_b32_e32 v108, 16, v27
	v_and_b32_e32 v109, 0xffff0000, v27
	s_waitcnt lgkmcnt(0)
	v_mul_f32_e32 v40, v110, v88
	v_mul_f32_e32 v41, v110, v89
	v_mul_f32_e32 v42, v110, v90
	v_mul_f32_e32 v44, v110, v92
	s_waitcnt lgkmcnt(0)
; #define LAS __attribute__((address_space(3)))
; #define LAS __attribute__((address_space(3)))
; __device__ __forceinline__ void rowwise_phase(const Args& a, LAS unsigned char* lds, bool from_partials, bool has_y, bool has_h, bool xin_bf, int xout_mode, ...
;     ...
;                 for (int h = 0; h < 4; ++h) { float ss = 0.f;
; #pragma unroll
;                     for (int j = 0; j < 2; ++j)
; #pragma unroll
;                         for (int e = 0; e < 8; ++e) ss += v[h][j][e] * v[h][j][e];
;                     rstd[h] = __builtin_amdgcn_rsqf(wave_sum(ss) * (1.0f / DM) + EPS); }
; #pragma unroll
;                 for (int j = 0; j < 2; ++j) { const LAS float* gsp = vec + DM + 8 * lane + 512 * j; const LAS float* shp = vec + 2 * DM + 8 * lane + 512 * j;
;                     const f32x4 a0 = *(const LAS f32x4*)gsp, a1 = *(const LAS f32x4*)(gsp + 4), b0 = *(const LAS f32x4*)shp, b1 = *(const LAS f32x4*)(shp + 4);
;                     const float gs[8] = {a0.x, a0.y, a0.z, a0.w, a1.x, a1.y, a1.z, a1.w}, sh[8] = {b0.x, b0.y, b0.z, b0.w, b1.x, b1.y, b1.z, b1.w};
	v_fmamk_f32 v24, v24, 0x3a800000, v194
	v_rsq_f32_e32 v111, v24
	v_mul_f32_e32 v24, v52, v52
	v_fmac_f32_e32 v24, v58, v58
	v_fmac_f32_e32 v24, v59, v59
	v_fmac_f32_e32 v24, v53, v53
	v_fmac_f32_e32 v24, v63, v63
	v_fmac_f32_e32 v24, v54, v54
	v_fmac_f32_e32 v24, v71, v71
	v_fmac_f32_e32 v24, v55, v55
	v_fmac_f32_e32 v24, v79, v79
	v_fmac_f32_e32 v24, v48, v48
	v_fmac_f32_e32 v24, v84, v84
	v_fmac_f32_e32 v24, v49, v49
	v_fmac_f32_e32 v24, v85, v85
	v_fmac_f32_e32 v24, v50, v50
	v_fmac_f32_e32 v24, v97, v97
	v_fmac_f32_e32 v24, v51, v51
	s_nop 1
	v_add_f32_dpp v25, v24, v24 quad_perm:[1,0,3,2] row_mask:0xf bank_mask:0xf
	v_mul_f32_e32 v43, v110, v91
	v_mul_f32_e32 v45, v110, v93
	v_mul_f32_e32 v88, v110, v94
	v_mul_f32_e32 v89, v110, v95
	s_waitcnt lgkmcnt(0)
	s_nop 1
	v_add_f32_dpp v24, v25, v25 quad_perm:[2,3,0,1] row_mask:0xf bank_mask:0xf
	s_nop 1
	v_add_f32_dpp v24, v24, v24 row_half_mirror row_mask:0xf bank_mask:0xf
	s_nop 1
	v_add_f32_dpp v24, v24, v24 row_mirror row_mask:0xf bank_mask:0xf
	s_nop 1
	v_add_f32_dpp v24, v24, v24 row_bcast:15 row_mask:0xa bank_mask:0xf
	s_nop 1
	v_add_f32_dpp v24, v24, v24 row_bcast:31 row_mask:0xc bank_mask:0xf
	s_nop 1
	v_readlane_b32 s100, v24, 63
	s_nop 1
	v_mov_b32_e32 v24, s100
	s_waitcnt lgkmcnt(0)
	s_waitcnt lgkmcnt(0)
	s_waitcnt lgkmcnt(0)
	s_waitcnt lgkmcnt(0)
	s_waitcnt lgkmcnt(0)
	v_fmamk_f32 v24, v24, 0x3a800000, v194
	v_rsq_f32_e32 v112, v24
	v_mul_f32_e32 v24, v99, v99
	v_fmac_f32_e32 v24, v98, v98
	v_fmac_f32_e32 v24, v100, v100
	v_fmac_f32_e32 v24, v101, v101
	v_fmac_f32_e32 v24, v102, v102
	v_fmac_f32_e32 v24, v46, v46
	v_fmac_f32_e32 v24, v103, v103
	v_fmac_f32_e32 v24, v47, v47
	v_fmac_f32_e32 v24, v86, v86
	v_fmac_f32_e32 v24, v87, v87
	v_fmac_f32_e32 v24, v104, v104
	v_fmac_f32_e32 v24, v105, v105
	v_fmac_f32_e32 v24, v106, v106
	v_fmac_f32_e32 v24, v107, v107
	v_fmac_f32_e32 v24, v108, v108
	v_fmac_f32_e32 v24, v109, v109
	s_nop 1
	v_add_f32_dpp v25, v24, v24 quad_perm:[1,0,3,2] row_mask:0xf bank_mask:0xf
	v_mul_f32_e32 v55, v112, v55
	s_waitcnt lgkmcnt(0)
	s_nop 1
	v_add_f32_dpp v24, v25, v25 quad_perm:[2,3,0,1] row_mask:0xf bank_mask:0xf
	s_nop 1
	v_add_f32_dpp v24, v24, v24 row_half_mirror row_mask:0xf bank_mask:0xf
	s_nop 1
	v_add_f32_dpp v24, v24, v24 row_mirror row_mask:0xf bank_mask:0xf
	s_nop 1
	v_add_f32_dpp v24, v24, v24 row_bcast:15 row_mask:0xa bank_mask:0xf
	s_nop 1
	v_add_f32_dpp v24, v24, v24 row_bcast:31 row_mask:0xc bank_mask:0xf
	s_nop 1
	v_readlane_b32 s100, v24, 63
	s_nop 1
	v_mov_b32_e32 v24, s100
	s_waitcnt lgkmcnt(0)
	s_waitcnt lgkmcnt(0)
	s_waitcnt lgkmcnt(0)
	s_waitcnt lgkmcnt(0)
	s_waitcnt lgkmcnt(0)
	v_fmamk_f32 v24, v24, 0x3a800000, v194
	v_rsq_f32_e32 v113, v24
	ds_read_b128 v[24:27], v0 offset:4096
	ds_read_b128 v[28:31], v0 offset:4112
	ds_read_b128 v[32:35], v0 offset:8192
	ds_read_b128 v[36:39], v0 offset:8208
	s_waitcnt lgkmcnt(1)
	v_fma_f32 v40, v40, v24, v32
	v_fma_f32 v41, v41, v25, v33
	v_fma_f32 v42, v42, v26, v34
	s_waitcnt lgkmcnt(0)
; #define LAS __attribute__((address_space(3)))
; #define LAS __attribute__((address_space(3)))
; __device__ __forceinline__ v4u pack8(const float (&f)[8]) { return (v4u){pk2(f[0], f[1]), pk2(f[2], f[3]), pk2(f[4], f[5]), pk2(f[6], f[7])}; }
; __device__ __forceinline__ void rowwise_phase(const Args& a, LAS unsigned char* lds, bool from_partials, bool has_y, bool has_h, bool xin_bf, int xout_mode, ...
;     ...
;                 for (int j = 0; j < 2; ++j) { const LAS float* gsp = vec + DM + 8 * lane + 512 * j; const LAS float* shp = vec + 2 * DM + 8 * lane + 512 * j;
;                     const f32x4 a0 = *(const LAS f32x4*)gsp, a1 = *(const LAS f32x4*)(gsp + 4), b0 = *(const LAS f32x4*)shp, b1 = *(const LAS f32x4*)(shp + 4);
;                     const float gs[8] = {a0.x, a0.y, a0.z, a0.w, a1.x, a1.y, a1.z, a1.w}, sh[8] = {b0.x, b0.y, b0.z, b0.w, b1.x, b1.y, b1.z, b1.w};
; #pragma unroll
;                     for (int h = 0; h < 4; ++h) { float hv[8];
; #pragma unroll
;                         for (int e = 0; e < 8; ++e) hv[e] = v[h][j][e] * rstd[h] * gs[e] + sh[e];
;                         *(v4u*)(hout + ((size_t)tile * 256 + r + h) * DM + 8 * lane + 512 * j) = pack8(hv); } }
;             }
;         }
	v_fma_f32 v44, v44, v28, v36
	v_fma_f32 v43, v43, v27, v35
	v_fma_f32 v45, v45, v29, v37
	v_cvt_pk_bf16_f32 v40, v40, v41
	v_cvt_pk_bf16_f32 v41, v42, v43
	v_cvt_pk_bf16_f32 v42, v44, v45
	v_add_co_u32_e32 v44, vcc, s4, v10
	v_fma_f32 v88, v88, v30, v38
	s_nop 0
	v_addc_co_u32_e32 v45, vcc, 0, v11, vcc
	v_add_co_u32_e32 v10, vcc, s5, v10
	v_fma_f32 v89, v89, v31, v39
	s_nop 0
	v_addc_co_u32_e32 v11, vcc, 0, v11, vcc
	v_cvt_pk_bf16_f32 v43, v88, v89
	global_store_dwordx4 v[10:11], v[40:43], off offset:-4096
	v_fma_f32 v55, v55, v31, v39
	v_cmp_lt_i32_e32 vcc, s33, v23
	v_mul_f32_e32 v40, v111, v60
	v_fma_f32 v40, v40, v24, v32
	v_mul_f32_e32 v41, v111, v64
	v_mul_f32_e32 v42, v111, v65
	v_mul_f32_e32 v43, v111, v67
	v_fma_f32 v41, v41, v25, v33
	v_fma_f32 v42, v42, v26, v34
	v_fma_f32 v43, v43, v27, v35
	v_mul_f32_e32 v60, v111, v74
	v_mul_f32_e32 v64, v111, v76
	v_mul_f32_e32 v65, v111, v77
	v_mul_f32_e32 v67, v111, v78
	v_cvt_pk_bf16_f32 v40, v40, v41
	v_fma_f32 v60, v60, v28, v36
	v_fma_f32 v64, v64, v29, v37
	v_fma_f32 v65, v65, v30, v38
	v_fma_f32 v67, v67, v31, v39
	v_cvt_pk_bf16_f32 v41, v42, v43
	v_cvt_pk_bf16_f32 v42, v60, v64
	v_cvt_pk_bf16_f32 v43, v65, v67
	global_store_dwordx4 v[44:45], v[40:43], off offset:2048
	s_or_b64 s[54:55], vcc, s[54:55]
	s_nop 0
	v_mul_f32_e32 v40, v112, v58
	v_fma_f32 v40, v40, v24, v32
	v_mul_f32_e32 v41, v112, v52
	v_mul_f32_e32 v42, v112, v59
	v_mul_f32_e32 v43, v112, v53
	v_fma_f32 v41, v41, v25, v33
	v_fma_f32 v42, v42, v26, v34
	v_fma_f32 v43, v43, v27, v35
	v_mul_f32_e32 v52, v112, v63
	v_mul_f32_e32 v53, v112, v54
	v_mul_f32_e32 v54, v112, v71
	v_cvt_pk_bf16_f32 v40, v40, v41
	v_fma_f32 v52, v52, v28, v36
	v_fma_f32 v53, v53, v29, v37
	v_fma_f32 v54, v54, v30, v38
	v_cvt_pk_bf16_f32 v41, v42, v43
	v_cvt_pk_bf16_f32 v42, v52, v53
	v_cvt_pk_bf16_f32 v43, v54, v55
	global_store_dwordx4 v[10:11], v[40:43], off
	v_mul_f32_e32 v52, v110, v96
	v_mul_f32_e32 v53, v110, v83
	v_mul_f32_e32 v40, v113, v98
	v_fma_f32 v24, v24, v40, v32
	v_mul_f32_e32 v32, v113, v99
	v_fma_f32 v25, v25, v32, v33
	v_mul_f32_e32 v32, v113, v100
	v_fma_f32 v26, v26, v32, v34
	v_mul_f32_e32 v32, v113, v101
	v_fmac_f32_e32 v35, v27, v32
	v_mul_f32_e32 v27, v113, v102
	v_fma_f32 v27, v28, v27, v36
	v_mul_f32_e32 v28, v113, v46
	v_fma_f32 v28, v29, v28, v37
	v_mul_f32_e32 v29, v113, v103
	v_fma_f32 v29, v30, v29, v38
	v_mul_f32_e32 v30, v113, v47
	v_fmac_f32_e32 v39, v31, v30
	v_cvt_pk_bf16_f32 v24, v24, v25
	v_cvt_pk_bf16_f32 v25, v26, v35
	v_cvt_pk_bf16_f32 v26, v27, v28
	v_cvt_pk_bf16_f32 v27, v29, v39
	global_store_dwordx4 v[10:11], v[24:27], off offset:2048
	ds_read_b128 v[24:27], v0 offset:6144
	ds_read_b128 v[28:31], v0 offset:6160
	ds_read_b128 v[32:35], v0 offset:10240
	ds_read_b128 v[36:39], v0 offset:10256
	v_mul_f32_e32 v40, v110, v72
	v_mul_f32_e32 v41, v110, v73
	v_mul_f32_e32 v42, v110, v75
	s_waitcnt lgkmcnt(1)
	v_fma_f32 v40, v40, v24, v32
	v_mul_f32_e32 v43, v110, v80
	v_fma_f32 v41, v41, v25, v33
	v_fma_f32 v42, v42, v26, v34
	v_fma_f32 v43, v43, v27, v35
	v_mul_f32_e32 v46, v110, v81
	v_mul_f32_e32 v47, v110, v82
	v_cvt_pk_bf16_f32 v40, v40, v41
	s_waitcnt lgkmcnt(0)
	v_fma_f32 v46, v46, v28, v36
	v_fma_f32 v47, v47, v29, v37
	v_fma_f32 v52, v52, v30, v38
	v_fma_f32 v53, v53, v31, v39
	v_cvt_pk_bf16_f32 v41, v42, v43
	v_cvt_pk_bf16_f32 v42, v46, v47
	v_cvt_pk_bf16_f32 v43, v52, v53
	global_store_dwordx4 v[44:45], v[40:43], off offset:1024
	v_mul_f32_e32 v46, v111, v66
	v_mul_f32_e32 v47, v111, v68
	v_mul_f32_e32 v40, v111, v56
	v_fma_f32 v40, v40, v24, v32
	v_mul_f32_e32 v41, v111, v57
	v_mul_f32_e32 v42, v111, v61
	v_mul_f32_e32 v43, v111, v62
	v_fma_f32 v41, v41, v25, v33
	v_fma_f32 v42, v42, v26, v34
	v_fma_f32 v43, v43, v27, v35
	v_mul_f32_e32 v52, v111, v69
	v_mul_f32_e32 v53, v111, v70
	v_cvt_pk_bf16_f32 v40, v40, v41
	v_fma_f32 v46, v46, v28, v36
	v_fma_f32 v47, v47, v29, v37
	v_fma_f32 v52, v52, v30, v38
	v_fma_f32 v53, v53, v31, v39
	v_cvt_pk_bf16_f32 v41, v42, v43
	v_cvt_pk_bf16_f32 v42, v46, v47
	v_cvt_pk_bf16_f32 v43, v52, v53
	global_store_dwordx4 v[44:45], v[40:43], off offset:3072
	v_mul_f32_e32 v44, v112, v85
	v_mul_f32_e32 v45, v112, v50
	v_mul_f32_e32 v40, v112, v79
	v_fma_f32 v40, v40, v24, v32
	v_mul_f32_e32 v41, v112, v48
	v_mul_f32_e32 v42, v112, v84
	v_mul_f32_e32 v43, v112, v49
	v_fma_f32 v41, v41, v25, v33
	v_fma_f32 v42, v42, v26, v34
	v_fma_f32 v43, v43, v27, v35
	v_mul_f32_e32 v46, v112, v97
	v_mul_f32_e32 v47, v112, v51
	v_cvt_pk_bf16_f32 v40, v40, v41
	v_fma_f32 v44, v44, v28, v36
	v_fma_f32 v45, v45, v29, v37
	v_fma_f32 v46, v46, v30, v38
	v_fma_f32 v47, v47, v31, v39
	v_cvt_pk_bf16_f32 v41, v42, v43
	v_cvt_pk_bf16_f32 v42, v44, v45
	v_cvt_pk_bf16_f32 v43, v46, v47
	global_store_dwordx4 v[10:11], v[40:43], off offset:1024
	s_nop 1
	v_mul_f32_e32 v40, v113, v86
	v_fma_f32 v24, v40, v24, v32
	v_mul_f32_e32 v32, v113, v87
	v_fma_f32 v25, v32, v25, v33
	v_mul_f32_e32 v32, v113, v104
	v_fma_f32 v26, v32, v26, v34
	v_mul_f32_e32 v32, v113, v105
	v_fmac_f32_e32 v35, v32, v27
	v_mul_f32_e32 v27, v113, v106
	v_fma_f32 v27, v27, v28, v36
	v_mul_f32_e32 v28, v113, v107
	v_fma_f32 v28, v28, v29, v37
	v_mul_f32_e32 v29, v113, v108
	v_fma_f32 v29, v29, v30, v38
	v_mul_f32_e32 v30, v113, v109
	v_fmac_f32_e32 v39, v30, v31
	v_cvt_pk_bf16_f32 v24, v24, v25
	v_cvt_pk_bf16_f32 v25, v26, v35
	v_cvt_pk_bf16_f32 v26, v27, v28
	v_cvt_pk_bf16_f32 v27, v29, v39
	global_store_dwordx4 v[10:11], v[24:27], off offset:3072
	s_andn2_b64 exec, exec, s[54:55]
	s_cbranch_execnz .LBB0_517
	s_branch .LBB0_504

; #define LAS __attribute__((address_space(3)))
; #define LAS __attribute__((address_space(3)))
; __device__ __forceinline__ void rowwise_phase(const Args& a, LAS unsigned char* lds, bool from_partials, bool has_y, bool has_h, bool xin_bf, int xout_mode, ...
;     ...
;         for (int r = wave * 4; r < 256; r += 32) {
;             float v[4][2][8]; v4u yv[4][2];
; #pragma unroll
;             for (int h = 0; h < 4; ++h)
; #pragma unroll
;                 for (int j = 0; j < 2; ++j) { const size_t off = ((size_t)tile * 256 + r + h) * DM + 8 * lane + 512 * j;
;                     if (xin_bf) unpack8(__builtin_nontemporal_load((const v4u*)((const bf16*)xin + off)), v[h][j]);
;                     else { const f32x4 p0 = __builtin_nontemporal_load((const f32x4*)((const float*)xin + off)), p1 = __builtin_nontemporal_load((const f32x4*)((const float*)xin + off + 4));
;                         v[h][j][0] = p0.x; v[h][j][1] = p0.y; v[h][j][2] = p0.z; v[h][j][3] = p0.w; v[h][j][4] = p1.x; v[h][j][5] = p1.y; v[h][j][6] = p1.z; v[h][j][7] = p1.w; }
;                     yv[h][j] = has_y ? __builtin_nontemporal_load((const v4u*)(y + off)) : (v4u){0u, 0u, 0u, 0u}; }
;             if (has_y) {
;                 float rstd[4];
; #pragma unroll
;                 for (int h = 0; h < 4; ++h) { float ss = 0.f;
; #pragma unroll
;                     for (int j = 0; j < 2; ++j) { float yf[8]; unpack8(yv[h][j], yf);
; #pragma unroll
;                         for (int e = 0; e < 8; ++e) ss += yf[e] * yf[e]; }
;                     rstd[h] = __builtin_amdgcn_rsqf(wave_sum(ss) * (1.0f / DM) + EPS); }
; #pragma unroll
;                 for (int j = 0; j < 2; ++j) { const LAS float* gpp = vec + 8 * lane + 512 * j; const f32x4 g0 = *(const LAS f32x4*)gpp, g1 = *(const LAS f32x4*)(gpp + 4);
;                     const float gp[8] = {g0.x, g0.y, g0.z, g0.w, g1.x, g1.y, g1.z, g1.w};
; #pragma unroll
;                     for (int h = 0; h < 4; ++h) { float yf[8]; unpack8(yv[h][j], yf);
; #pragma unroll
;                         for (int e = 0; e < 8; ++e) v[h][j][e] += gp[e] * (yf[e] * rstd[h]); } }
.LBB0_727:
	v_lshl_add_u64 v[92:93], v[84:85], 0, v[90:91]
	v_add_co_u32_e32 v18, vcc, 0x2a000000, v92
	v_add_u32_e32 v144, 0, v134
	s_nop 0
	v_addc_co_u32_e32 v19, vcc, 0, v93, vcc
	v_add_co_u32_e32 v20, vcc, 0xc000000, v92
	global_load_dwordx4 v[6:9], v[18:19], off nt
	s_nop 0
	v_addc_co_u32_e32 v21, vcc, 0, v93, vcc
	global_load_dwordx4 v[2:5], v[20:21], off nt
	global_load_dwordx4 v[10:13], v[18:19], off offset:1024 nt
	global_load_dwordx4 v[14:17], v[20:21], off offset:1024 nt
	global_load_dwordx4 v[30:33], v[18:19], off offset:2048 nt
	global_load_dwordx4 v[26:29], v[20:21], off offset:2048 nt
	global_load_dwordx4 v[54:57], v[18:19], off offset:3072 nt
	global_load_dwordx4 v[50:53], v[20:21], off offset:3072 nt
	v_add_co_u32_e32 v18, vcc, s69, v92
	s_mov_b64 s[16:17], -1
	s_nop 0
	v_addc_co_u32_e32 v19, vcc, 0, v93, vcc
	v_add_co_u32_e32 v20, vcc, s68, v92
	global_load_dwordx4 v[62:65], v[18:19], off nt
	s_nop 0
	v_addc_co_u32_e32 v21, vcc, 0, v93, vcc
	global_load_dwordx4 v[58:61], v[20:21], off nt
	global_load_dwordx4 v[70:73], v[18:19], off offset:1024 nt
	global_load_dwordx4 v[66:69], v[20:21], off offset:1024 nt
	global_load_dwordx4 v[42:45], v[18:19], off offset:2048 nt
	global_load_dwordx4 v[46:49], v[20:21], off offset:2048 nt
	global_load_dwordx4 v[38:41], v[18:19], off offset:3072 nt
	global_load_dwordx4 v[34:37], v[20:21], off offset:3072 nt
	ds_read_b128 v[22:25], v144
	ds_read_b128 v[18:21], v144 offset:16
	s_and_b64 vcc, exec, s[20:21]
	s_waitcnt vmcnt(14)
	v_and_b32_e32 v157, 0xffff0000, v3
	v_lshlrev_b32_e32 v156, 16, v3
	v_and_b32_e32 v3, 0xffff0000, v2
	v_lshlrev_b32_e32 v2, 16, v2
	v_pk_mul_f32 v[160:161], v[2:3], v[2:3]
	v_pk_mul_f32 v[158:159], v[156:157], v[156:157]
	v_add_f32_e32 v145, v160, v161
	v_and_b32_e32 v151, 0xffff0000, v5
	v_lshlrev_b32_e32 v150, 16, v5
	v_and_b32_e32 v5, 0xffff0000, v4
	v_lshlrev_b32_e32 v4, 16, v4
	v_add_f32_e32 v145, v158, v145
	v_pk_mul_f32 v[152:153], v[4:5], v[4:5]
	v_add_f32_e32 v145, v159, v145
	v_add_f32_e32 v145, v152, v145
	s_waitcnt vmcnt(12)
	v_and_b32_e32 v131, 0xffff0000, v15
	v_lshlrev_b32_e32 v130, 16, v15
	v_and_b32_e32 v147, 0xffff0000, v14
	v_lshlrev_b32_e32 v146, 16, v14
	v_pk_mul_f32 v[14:15], v[150:151], v[150:151]
	v_add_f32_e32 v145, v153, v145
	v_add_f32_e32 v14, v14, v145
	v_and_b32_e32 v129, 0xffff0000, v11
	v_lshlrev_b32_e32 v128, 16, v11
	v_and_b32_e32 v133, 0xffff0000, v10
	v_lshlrev_b32_e32 v132, 16, v10
	v_pk_mul_f32 v[10:11], v[146:147], v[146:147]
	v_add_f32_e32 v14, v15, v14
	v_add_f32_e32 v10, v10, v14
	v_and_b32_e32 v121, 0xffff0000, v17
	v_lshlrev_b32_e32 v120, 16, v17
	v_and_b32_e32 v127, 0xffff0000, v16
	v_lshlrev_b32_e32 v126, 16, v16
	v_pk_mul_f32 v[16:17], v[130:131], v[130:131]
	v_add_f32_e32 v10, v11, v10
	v_add_f32_e32 v10, v16, v10
	v_and_b32_e32 v119, 0xffff0000, v13
	v_lshlrev_b32_e32 v118, 16, v13
	v_and_b32_e32 v125, 0xffff0000, v12
	v_lshlrev_b32_e32 v124, 16, v12
	v_pk_mul_f32 v[12:13], v[126:127], v[126:127]
	v_add_f32_e32 v10, v17, v10
	v_add_f32_e32 v10, v12, v10
	v_pk_mul_f32 v[122:123], v[120:121], v[120:121]
	v_add_f32_e32 v10, v13, v10
	v_add_f32_e32 v10, v122, v10
	v_add_f32_e32 v10, v123, v10
	s_nop 1
	v_add_f32_dpp v11, v10, v10 quad_perm:[1,0,3,2] row_mask:0xf bank_mask:0xf
	v_and_b32_e32 v155, 0xffff0000, v7
	v_lshlrev_b32_e32 v154, 16, v7
	v_and_b32_e32 v7, 0xffff0000, v6
	v_lshlrev_b32_e32 v6, 16, v6
	s_waitcnt lgkmcnt(0)
	s_nop 1
	v_add_f32_dpp v10, v11, v11 quad_perm:[2,3,0,1] row_mask:0xf bank_mask:0xf
	s_nop 1
	v_add_f32_dpp v10, v10, v10 row_half_mirror row_mask:0xf bank_mask:0xf
	s_nop 1
	v_add_f32_dpp v10, v10, v10 row_mirror row_mask:0xf bank_mask:0xf
	s_nop 1
	v_add_f32_dpp v10, v10, v10 row_bcast:15 row_mask:0xa bank_mask:0xf
	s_nop 1
	v_add_f32_dpp v10, v10, v10 row_bcast:31 row_mask:0xc bank_mask:0xf
	s_nop 1
	v_readlane_b32 s100, v10, 63
	s_nop 1
	v_mov_b32_e32 v10, s100
	s_waitcnt vmcnt(3)
	v_lshlrev_b32_e32 v94, 16, v42
	v_and_b32_e32 v95, 0xffff0000, v42
	s_waitcnt vmcnt(2)
	v_lshlrev_b32_e32 v98, 16, v46
	v_and_b32_e32 v99, 0xffff0000, v46
	s_waitcnt lgkmcnt(0)
	v_lshlrev_b32_e32 v96, 16, v43
	v_and_b32_e32 v97, 0xffff0000, v43
	v_lshlrev_b32_e32 v102, 16, v47
	v_and_b32_e32 v103, 0xffff0000, v47
	s_waitcnt lgkmcnt(0)
	v_lshlrev_b32_e32 v100, 16, v44
	v_and_b32_e32 v101, 0xffff0000, v44
	v_lshlrev_b32_e32 v106, 16, v48
	v_and_b32_e32 v107, 0xffff0000, v48
	s_waitcnt lgkmcnt(0)
	v_lshlrev_b32_e32 v104, 16, v45
	v_and_b32_e32 v105, 0xffff0000, v45
	v_lshlrev_b32_e32 v108, 16, v49
	v_and_b32_e32 v109, 0xffff0000, v49
	s_waitcnt lgkmcnt(0)
	ds_read_b128 v[46:49], v144 offset:2048
	ds_read_b128 v[42:45], v144 offset:2064
	v_and_b32_e32 v149, 0xffff0000, v9
	v_lshlrev_b32_e32 v148, 16, v9
	v_and_b32_e32 v9, 0xffff0000, v8
	s_waitcnt lgkmcnt(2)
	v_fmamk_f32 v10, v10, 0x3a800000, v194
	v_rsq_f32_e32 v122, v10
	v_lshlrev_b32_e32 v8, 16, v8
	v_pk_mul_f32 v[110:111], v[98:99], v[98:99]
	v_pk_mul_f32 v[112:113], v[102:103], v[102:103]
	v_pk_mul_f32 v[2:3], v[122:123], v[2:3] op_sel_hi:[0,1]
	v_pk_fma_f32 v[14:15], v[2:3], v[22:23], v[6:7]
	v_pk_mul_f32 v[2:3], v[122:123], v[156:157] op_sel_hi:[0,1]
	v_and_b32_e32 v157, 0xffff0000, v27
	v_lshlrev_b32_e32 v156, 16, v27
	v_and_b32_e32 v27, 0xffff0000, v26
	v_lshlrev_b32_e32 v26, 16, v26
	v_pk_mul_f32 v[160:161], v[26:27], v[26:27]
	v_pk_fma_f32 v[16:17], v[2:3], v[24:25], v[154:155]
	v_pk_mul_f32 v[2:3], v[122:123], v[4:5] op_sel_hi:[0,1]
	v_pk_mul_f32 v[158:159], v[156:157], v[156:157]
	v_add_f32_e32 v145, v160, v161
	v_pk_fma_f32 v[10:11], v[2:3], v[18:19], v[8:9]
	v_pk_mul_f32 v[2:3], v[122:123], v[150:151] op_sel_hi:[0,1]
	v_and_b32_e32 v151, 0xffff0000, v29
	v_lshlrev_b32_e32 v150, 16, v29
	v_and_b32_e32 v29, 0xffff0000, v28
	v_lshlrev_b32_e32 v28, 16, v28
	v_add_f32_e32 v145, v158, v145
	v_pk_fma_f32 v[12:13], v[2:3], v[20:21], v[148:149]
	v_pk_mul_f32 v[2:3], v[122:123], v[146:147] op_sel_hi:[0,1]
	v_pk_mul_f32 v[152:153], v[28:29], v[28:29]
	v_add_f32_e32 v145, v159, v145
	s_waitcnt lgkmcnt(1)
; #define LAS __attribute__((address_space(3)))
; #define LAS __attribute__((address_space(3)))
; __device__ __forceinline__ void rowwise_phase(const Args& a, LAS unsigned char* lds, bool from_partials, bool has_y, bool has_h, bool xin_bf, int xout_mode, ...
;     ...
;                 for (int h = 0; h < 4; ++h) { float ss = 0.f;
; #pragma unroll
;                     for (int j = 0; j < 2; ++j) { float yf[8]; unpack8(yv[h][j], yf);
; #pragma unroll
;                         for (int e = 0; e < 8; ++e) ss += yf[e] * yf[e]; }
;                     rstd[h] = __builtin_amdgcn_rsqf(wave_sum(ss) * (1.0f / DM) + EPS); }
; #pragma unroll
;                 for (int j = 0; j < 2; ++j) { const LAS float* gpp = vec + 8 * lane + 512 * j; const f32x4 g0 = *(const LAS f32x4*)gpp, g1 = *(const LAS f32x4*)(gpp + 4);
;                     const float gp[8] = {g0.x, g0.y, g0.z, g0.w, g1.x, g1.y, g1.z, g1.w};
; #pragma unroll
;                     for (int h = 0; h < 4; ++h) { float yf[8]; unpack8(yv[h][j], yf);
; #pragma unroll
;                         for (int e = 0; e < 8; ++e) v[h][j][e] += gp[e] * (yf[e] * rstd[h]); } }
	v_pk_fma_f32 v[6:7], v[2:3], v[46:47], v[132:133]
	v_pk_mul_f32 v[2:3], v[122:123], v[130:131] op_sel_hi:[0,1]
	v_add_f32_e32 v145, v152, v145
	v_pk_fma_f32 v[8:9], v[2:3], v[48:49], v[128:129]
	v_pk_mul_f32 v[2:3], v[122:123], v[126:127] op_sel_hi:[0,1]
	v_and_b32_e32 v127, 0xffff0000, v55
	v_lshlrev_b32_e32 v126, 16, v55
	v_and_b32_e32 v133, 0xffff0000, v54
	v_lshlrev_b32_e32 v132, 16, v54
	v_pk_mul_f32 v[54:55], v[150:151], v[150:151]
	v_add_f32_e32 v145, v153, v145
	v_and_b32_e32 v147, 0xffff0000, v50
	v_lshlrev_b32_e32 v146, 16, v50
	v_add_f32_e32 v54, v54, v145
	v_and_b32_e32 v129, 0xffff0000, v51
	v_lshlrev_b32_e32 v128, 16, v51
	v_pk_mul_f32 v[50:51], v[146:147], v[146:147]
	v_add_f32_e32 v54, v55, v54
	v_pk_mul_f32 v[4:5], v[122:123], v[120:121] op_sel_hi:[0,1]
	v_add_f32_e32 v50, v50, v54
	s_waitcnt lgkmcnt(0)
	v_pk_fma_f32 v[4:5], v[4:5], v[44:45], v[118:119]
	v_and_b32_e32 v119, 0xffff0000, v57
	v_lshlrev_b32_e32 v118, 16, v57
	v_and_b32_e32 v123, 0xffff0000, v56
	v_lshlrev_b32_e32 v122, 16, v56
	v_pk_mul_f32 v[56:57], v[128:129], v[128:129]
	v_add_f32_e32 v50, v51, v50
	v_pk_fma_f32 v[2:3], v[2:3], v[42:43], v[124:125]
	v_and_b32_e32 v125, 0xffff0000, v52
	v_lshlrev_b32_e32 v124, 16, v52
	v_add_f32_e32 v50, v56, v50
	v_and_b32_e32 v121, 0xffff0000, v53
	v_lshlrev_b32_e32 v120, 16, v53
	v_pk_mul_f32 v[52:53], v[124:125], v[124:125]
	v_add_f32_e32 v50, v57, v50
	v_add_f32_e32 v50, v52, v50
	v_pk_mul_f32 v[130:131], v[120:121], v[120:121]
	v_add_f32_e32 v50, v53, v50
	v_add_f32_e32 v50, v130, v50
	v_add_f32_e32 v50, v131, v50
	s_nop 1
	v_add_f32_dpp v51, v50, v50 quad_perm:[1,0,3,2] row_mask:0xf bank_mask:0xf
	v_and_b32_e32 v155, 0xffff0000, v31
	v_lshlrev_b32_e32 v154, 16, v31
	v_and_b32_e32 v31, 0xffff0000, v30
	v_lshlrev_b32_e32 v30, 16, v30
	s_waitcnt lgkmcnt(0)
	s_nop 1
	v_add_f32_dpp v50, v51, v51 quad_perm:[2,3,0,1] row_mask:0xf bank_mask:0xf
	s_nop 1
	v_add_f32_dpp v50, v50, v50 row_half_mirror row_mask:0xf bank_mask:0xf
	s_nop 1
	v_add_f32_dpp v50, v50, v50 row_mirror row_mask:0xf bank_mask:0xf
	s_nop 1
	v_add_f32_dpp v50, v50, v50 row_bcast:15 row_mask:0xa bank_mask:0xf
	s_nop 1
	v_add_f32_dpp v50, v50, v50 row_bcast:31 row_mask:0xc bank_mask:0xf
	s_nop 1
	v_readlane_b32 s100, v50, 63
	s_nop 1
	v_mov_b32_e32 v50, s100
	v_and_b32_e32 v149, 0xffff0000, v33
	v_lshlrev_b32_e32 v148, 16, v33
	v_and_b32_e32 v33, 0xffff0000, v32
	v_lshlrev_b32_e32 v32, 16, v32
	s_waitcnt lgkmcnt(0)
	v_pk_mul_f32 v[114:115], v[106:107], v[106:107]
	v_pk_mul_f32 v[116:117], v[108:109], v[108:109]
	s_waitcnt lgkmcnt(0)
	s_waitcnt lgkmcnt(0)
	s_waitcnt lgkmcnt(0)
	s_waitcnt lgkmcnt(0)
	v_fmamk_f32 v50, v50, 0x3a800000, v194
	v_rsq_f32_e32 v130, v50
	s_nop 0
	v_pk_mul_f32 v[26:27], v[130:131], v[26:27] op_sel_hi:[0,1]
	v_pk_fma_f32 v[54:55], v[26:27], v[22:23], v[30:31]
	v_pk_mul_f32 v[26:27], v[130:131], v[156:157] op_sel_hi:[0,1]
	v_and_b32_e32 v157, 0xffff0000, v59
	v_lshlrev_b32_e32 v156, 16, v59
	v_and_b32_e32 v59, 0xffff0000, v58
	v_lshlrev_b32_e32 v58, 16, v58
	v_pk_mul_f32 v[160:161], v[58:59], v[58:59]
	v_pk_fma_f32 v[56:57], v[26:27], v[24:25], v[154:155]
	v_pk_mul_f32 v[26:27], v[130:131], v[28:29] op_sel_hi:[0,1]
	v_pk_mul_f32 v[158:159], v[156:157], v[156:157]
	v_add_f32_e32 v145, v160, v161
	v_pk_fma_f32 v[50:51], v[26:27], v[18:19], v[32:33]
	v_pk_mul_f32 v[26:27], v[130:131], v[150:151] op_sel_hi:[0,1]
	v_and_b32_e32 v151, 0xffff0000, v61
	v_lshlrev_b32_e32 v150, 16, v61
	v_and_b32_e32 v61, 0xffff0000, v60
	v_lshlrev_b32_e32 v60, 16, v60
	v_add_f32_e32 v145, v158, v145
	v_pk_mul_f32 v[152:153], v[60:61], v[60:61]
	v_add_f32_e32 v145, v159, v145
	v_pk_fma_f32 v[52:53], v[26:27], v[20:21], v[148:149]
	v_pk_mul_f32 v[26:27], v[130:131], v[146:147] op_sel_hi:[0,1]
	v_add_f32_e32 v145, v152, v145
	v_pk_fma_f32 v[30:31], v[26:27], v[46:47], v[132:133]
	v_pk_mul_f32 v[26:27], v[130:131], v[128:129] op_sel_hi:[0,1]
	v_and_b32_e32 v129, 0xffff0000, v71
	v_lshlrev_b32_e32 v128, 16, v71
	v_and_b32_e32 v133, 0xffff0000, v70
	v_lshlrev_b32_e32 v132, 16, v70
	v_pk_mul_f32 v[70:71], v[150:151], v[150:151]
	v_add_f32_e32 v145, v153, v145
	v_and_b32_e32 v147, 0xffff0000, v66
	v_lshlrev_b32_e32 v146, 16, v66
	v_add_f32_e32 v70, v70, v145
	v_pk_fma_f32 v[32:33], v[26:27], v[48:49], v[126:127]
	v_pk_mul_f32 v[26:27], v[130:131], v[124:125] op_sel_hi:[0,1]
	v_pk_mul_f32 v[28:29], v[130:131], v[120:121] op_sel_hi:[0,1]
	v_and_b32_e32 v131, 0xffff0000, v67
	v_lshlrev_b32_e32 v130, 16, v67
	v_pk_mul_f32 v[66:67], v[146:147], v[146:147]
	v_add_f32_e32 v70, v71, v70
	v_add_f32_e32 v66, v66, v70
	v_pk_fma_f32 v[26:27], v[26:27], v[42:43], v[122:123]
	v_pk_fma_f32 v[28:29], v[28:29], v[44:45], v[118:119]
	v_and_b32_e32 v119, 0xffff0000, v73
	v_lshlrev_b32_e32 v118, 16, v73
	v_and_b32_e32 v123, 0xffff0000, v72
	v_lshlrev_b32_e32 v122, 16, v72
	v_pk_mul_f32 v[72:73], v[130:131], v[130:131]
	v_add_f32_e32 v66, v67, v66
	v_and_b32_e32 v127, 0xffff0000, v68
	v_lshlrev_b32_e32 v126, 16, v68
	v_add_f32_e32 v66, v72, v66
	v_and_b32_e32 v121, 0xffff0000, v69
	v_lshlrev_b32_e32 v120, 16, v69
	v_pk_mul_f32 v[68:69], v[126:127], v[126:127]
	v_add_f32_e32 v66, v73, v66
	v_add_f32_e32 v66, v68, v66
	v_pk_mul_f32 v[124:125], v[120:121], v[120:121]
	v_add_f32_e32 v66, v69, v66
	v_add_f32_e32 v66, v124, v66
	v_add_f32_e32 v66, v125, v66
	s_nop 1
	v_add_f32_dpp v67, v66, v66 quad_perm:[1,0,3,2] row_mask:0xf bank_mask:0xf
	v_and_b32_e32 v155, 0xffff0000, v63
	v_lshlrev_b32_e32 v154, 16, v63
	v_and_b32_e32 v63, 0xffff0000, v62
	v_lshlrev_b32_e32 v62, 16, v62
	s_waitcnt lgkmcnt(0)
; #define LAS __attribute__((address_space(3)))
; #define LAS __attribute__((address_space(3)))
; __device__ __forceinline__ void rowwise_phase(const Args& a, LAS unsigned char* lds, bool from_partials, bool has_y, bool has_h, bool xin_bf, int xout_mode, ...
;     ...
;                 for (int h = 0; h < 4; ++h) { float ss = 0.f;
; #pragma unroll
;                     for (int j = 0; j < 2; ++j) { float yf[8]; unpack8(yv[h][j], yf);
; #pragma unroll
;                         for (int e = 0; e < 8; ++e) ss += yf[e] * yf[e]; }
;                     rstd[h] = __builtin_amdgcn_rsqf(wave_sum(ss) * (1.0f / DM) + EPS); }
; #pragma unroll
;                 for (int j = 0; j < 2; ++j) { const LAS float* gpp = vec + 8 * lane + 512 * j; const f32x4 g0 = *(const LAS f32x4*)gpp, g1 = *(const LAS f32x4*)(gpp + 4);
;                     const float gp[8] = {g0.x, g0.y, g0.z, g0.w, g1.x, g1.y, g1.z, g1.w};
; #pragma unroll
;                     for (int h = 0; h < 4; ++h) { float yf[8]; unpack8(yv[h][j], yf);
; #pragma unroll
;                         for (int e = 0; e < 8; ++e) v[h][j][e] += gp[e] * (yf[e] * rstd[h]); } }
;             }
;             if (xout_mode == 1) {
	s_nop 1
	v_add_f32_dpp v66, v67, v67 quad_perm:[2,3,0,1] row_mask:0xf bank_mask:0xf
	s_nop 1
	v_add_f32_dpp v66, v66, v66 row_half_mirror row_mask:0xf bank_mask:0xf
	s_nop 1
	v_add_f32_dpp v66, v66, v66 row_mirror row_mask:0xf bank_mask:0xf
	s_nop 1
	v_add_f32_dpp v66, v66, v66 row_bcast:15 row_mask:0xa bank_mask:0xf
	s_nop 1
	v_add_f32_dpp v66, v66, v66 row_bcast:31 row_mask:0xc bank_mask:0xf
	s_nop 1
	v_readlane_b32 s100, v66, 63
	s_nop 1
	v_mov_b32_e32 v66, s100
	v_and_b32_e32 v149, 0xffff0000, v65
	v_lshlrev_b32_e32 v148, 16, v65
	v_and_b32_e32 v65, 0xffff0000, v64
	v_lshlrev_b32_e32 v64, 16, v64
	s_waitcnt lgkmcnt(0)
	s_waitcnt lgkmcnt(0)
	s_waitcnt lgkmcnt(0)
	s_waitcnt lgkmcnt(0)
	s_waitcnt lgkmcnt(0)
	v_fmamk_f32 v66, v66, 0x3a800000, v194
	v_rsq_f32_e32 v124, v66
	s_nop 0
	v_pk_mul_f32 v[58:59], v[124:125], v[58:59] op_sel_hi:[0,1]
	v_pk_fma_f32 v[70:71], v[58:59], v[22:23], v[62:63]
	v_pk_mul_f32 v[58:59], v[124:125], v[156:157] op_sel_hi:[0,1]
	v_pk_fma_f32 v[72:73], v[58:59], v[24:25], v[154:155]
	v_pk_mul_f32 v[58:59], v[124:125], v[60:61] op_sel_hi:[0,1]
	v_pk_fma_f32 v[66:67], v[58:59], v[18:19], v[64:65]
	v_pk_mul_f32 v[58:59], v[124:125], v[150:151] op_sel_hi:[0,1]
	v_pk_fma_f32 v[68:69], v[58:59], v[20:21], v[148:149]
	v_pk_mul_f32 v[58:59], v[124:125], v[146:147] op_sel_hi:[0,1]
	v_pk_fma_f32 v[62:63], v[58:59], v[46:47], v[132:133]
	v_pk_mul_f32 v[58:59], v[124:125], v[130:131] op_sel_hi:[0,1]
	v_pk_fma_f32 v[64:65], v[58:59], v[48:49], v[128:129]
	s_waitcnt vmcnt(1)
	v_lshlrev_b32_e32 v128, 16, v40
	v_and_b32_e32 v129, 0xffff0000, v40
	v_add_f32_e32 v40, v110, v111
	v_add_f32_e32 v40, v112, v40
	v_add_f32_e32 v40, v113, v40
	v_add_f32_e32 v40, v114, v40
	v_add_f32_e32 v40, v115, v40
	v_pk_mul_f32 v[58:59], v[124:125], v[126:127] op_sel_hi:[0,1]
	v_pk_mul_f32 v[60:61], v[124:125], v[120:121] op_sel_hi:[0,1]
	s_waitcnt vmcnt(0)
	v_lshlrev_b32_e32 v120, 16, v34
	v_and_b32_e32 v121, 0xffff0000, v34
	v_add_f32_e32 v40, v116, v40
	v_pk_fma_f32 v[58:59], v[58:59], v[42:43], v[122:123]
	v_pk_mul_f32 v[122:123], v[120:121], v[120:121]
	v_add_f32_e32 v40, v117, v40
	v_lshlrev_b32_e32 v126, 16, v35
	v_and_b32_e32 v127, 0xffff0000, v35
	v_add_f32_e32 v40, v122, v40
	v_pk_mul_f32 v[34:35], v[126:127], v[126:127]
	v_add_f32_e32 v40, v123, v40
	v_lshlrev_b32_e32 v130, 16, v36
	v_and_b32_e32 v131, 0xffff0000, v36
	v_add_f32_e32 v34, v34, v40
	v_pk_fma_f32 v[60:61], v[60:61], v[44:45], v[118:119]
	v_lshlrev_b32_e32 v118, 16, v38
	v_and_b32_e32 v119, 0xffff0000, v38
	v_lshlrev_b32_e32 v124, 16, v39
	v_and_b32_e32 v125, 0xffff0000, v39
	v_pk_mul_f32 v[38:39], v[130:131], v[130:131]
	v_add_f32_e32 v34, v35, v34
	v_lshlrev_b32_e32 v146, 16, v37
	v_and_b32_e32 v147, 0xffff0000, v37
	v_add_f32_e32 v34, v38, v34
	v_pk_mul_f32 v[36:37], v[146:147], v[146:147]
	v_add_f32_e32 v34, v39, v34
	v_add_f32_e32 v34, v36, v34
	v_add_f32_e32 v34, v37, v34
	s_nop 1
	v_add_f32_dpp v35, v34, v34 quad_perm:[1,0,3,2] row_mask:0xf bank_mask:0xf
	v_lshlrev_b32_e32 v132, 16, v41
	v_and_b32_e32 v133, 0xffff0000, v41
	s_waitcnt lgkmcnt(0)
	s_nop 1
	v_add_f32_dpp v34, v35, v35 quad_perm:[2,3,0,1] row_mask:0xf bank_mask:0xf
	s_nop 1
	v_add_f32_dpp v34, v34, v34 row_half_mirror row_mask:0xf bank_mask:0xf
	s_nop 1
	v_add_f32_dpp v34, v34, v34 row_mirror row_mask:0xf bank_mask:0xf
	s_nop 1
	v_add_f32_dpp v34, v34, v34 row_bcast:15 row_mask:0xa bank_mask:0xf
	s_nop 1
	v_add_f32_dpp v34, v34, v34 row_bcast:31 row_mask:0xc bank_mask:0xf
	s_nop 1
	v_readlane_b32 s100, v34, 63
	s_nop 1
	v_mov_b32_e32 v34, s100
	s_waitcnt lgkmcnt(0)
	s_waitcnt lgkmcnt(0)
	s_waitcnt lgkmcnt(0)
	s_waitcnt lgkmcnt(0)
	s_waitcnt lgkmcnt(0)
	v_fmamk_f32 v34, v34, 0x3a800000, v194
	v_rsq_f32_e32 v110, v34
	s_nop 0
	v_pk_mul_f32 v[34:35], v[110:111], v[98:99] op_sel_hi:[0,1]
	v_pk_fma_f32 v[38:39], v[22:23], v[34:35], v[94:95]
	v_pk_mul_f32 v[22:23], v[110:111], v[102:103] op_sel_hi:[0,1]
	v_pk_fma_f32 v[40:41], v[24:25], v[22:23], v[96:97]
	v_pk_mul_f32 v[22:23], v[110:111], v[106:107] op_sel_hi:[0,1]
	v_pk_fma_f32 v[34:35], v[18:19], v[22:23], v[100:101]
	v_pk_mul_f32 v[18:19], v[110:111], v[108:109] op_sel_hi:[0,1]
	v_pk_fma_f32 v[36:37], v[20:21], v[18:19], v[104:105]
	v_pk_mul_f32 v[18:19], v[110:111], v[120:121] op_sel_hi:[0,1]
	v_pk_fma_f32 v[22:23], v[46:47], v[18:19], v[118:119]
	v_pk_mul_f32 v[18:19], v[110:111], v[126:127] op_sel_hi:[0,1]
	v_pk_fma_f32 v[24:25], v[48:49], v[18:19], v[124:125]
	v_pk_mul_f32 v[18:19], v[110:111], v[130:131] op_sel_hi:[0,1]
	v_pk_mul_f32 v[20:21], v[110:111], v[146:147] op_sel_hi:[0,1]
	v_pk_fma_f32 v[18:19], v[42:43], v[18:19], v[128:129]
	v_pk_fma_f32 v[20:21], v[44:45], v[20:21], v[132:133]
	s_cbranch_vccnz .LBB0_730
	s_andn2_b64 vcc, exec, s[16:17]
	s_cbranch_vccz .LBB0_731

; __device__ __forceinline__ void rowwise_phase(const Args& a, LAS unsigned char* lds, bool from_partials, bool has_y, bool has_h, bool xin_bf, int xout_mode, ...
;     ...
;             if (has_h) {
;                 float rstd[4];
; #pragma unroll
;                 for (int h = 0; h < 4; ++h) { float ss = 0.f;
; #pragma unroll
;                     for (int j = 0; j < 2; ++j)
; #pragma unroll
;                         for (int e = 0; e < 8; ++e) ss += v[h][j][e] * v[h][j][e];
;                     rstd[h] = __builtin_amdgcn_rsqf(wave_sum(ss) * (1.0f / DM) + EPS); }
.LBB0_732:
	v_pk_mul_f32 v[42:43], v[14:15], v[14:15]
	v_pk_mul_f32 v[44:45], v[16:17], v[16:17]
	v_add_f32_e32 v42, v43, v42
	v_add_f32_e32 v42, v44, v42
	v_pk_mul_f32 v[46:47], v[10:11], v[10:11]
	v_add_f32_e32 v42, v45, v42
	v_add_f32_e32 v42, v46, v42
	v_pk_mul_f32 v[48:49], v[12:13], v[12:13]
	v_add_f32_e32 v42, v47, v42
	v_add_f32_e32 v42, v48, v42
	v_pk_mul_f32 v[94:95], v[6:7], v[6:7]
	v_add_f32_e32 v42, v49, v42
	v_add_f32_e32 v42, v94, v42
	v_pk_mul_f32 v[96:97], v[8:9], v[8:9]
	v_add_f32_e32 v42, v95, v42
	v_add_f32_e32 v42, v96, v42
	v_pk_mul_f32 v[98:99], v[2:3], v[2:3]
	v_add_f32_e32 v42, v97, v42
	v_add_f32_e32 v42, v98, v42
	v_pk_mul_f32 v[100:101], v[4:5], v[4:5]
	v_add_f32_e32 v42, v99, v42
	v_add_f32_e32 v42, v100, v42
	v_add_f32_e32 v42, v101, v42
	s_nop 1
	v_add_f32_dpp v43, v42, v42 quad_perm:[1,0,3,2] row_mask:0xf bank_mask:0xf
	v_pk_mul_f32 v[44:45], v[54:55], v[54:55]
	v_pk_mul_f32 v[46:47], v[56:57], v[56:57]
	v_pk_mul_f32 v[48:49], v[50:51], v[50:51]
	v_pk_mul_f32 v[94:95], v[52:53], v[52:53]
	s_waitcnt lgkmcnt(0)
	s_nop 1
	v_add_f32_dpp v42, v43, v43 quad_perm:[2,3,0,1] row_mask:0xf bank_mask:0xf
	s_nop 1
	v_add_f32_dpp v42, v42, v42 row_half_mirror row_mask:0xf bank_mask:0xf
	s_nop 1
	v_add_f32_dpp v42, v42, v42 row_mirror row_mask:0xf bank_mask:0xf
	s_nop 1
	v_add_f32_dpp v42, v42, v42 row_bcast:15 row_mask:0xa bank_mask:0xf
	s_nop 1
	v_add_f32_dpp v42, v42, v42 row_bcast:31 row_mask:0xc bank_mask:0xf
	s_nop 1
	v_readlane_b32 s100, v42, 63
	s_nop 1
	v_mov_b32_e32 v42, s100
	v_pk_mul_f32 v[96:97], v[30:31], v[30:31]
	v_pk_mul_f32 v[98:99], v[32:33], v[32:33]
	v_pk_mul_f32 v[100:101], v[26:27], v[26:27]
	v_pk_mul_f32 v[102:103], v[28:29], v[28:29]
	s_waitcnt lgkmcnt(0)
	s_waitcnt lgkmcnt(0)
	s_waitcnt lgkmcnt(0)
	s_waitcnt lgkmcnt(0)
	s_waitcnt lgkmcnt(0)
	v_add_f32_e32 v43, v45, v44
	v_add_f32_e32 v43, v46, v43
	v_add_f32_e32 v43, v47, v43
	v_add_f32_e32 v43, v48, v43
	v_add_f32_e32 v43, v49, v43
	v_add_f32_e32 v43, v94, v43
	v_add_f32_e32 v43, v95, v43
	v_add_f32_e32 v43, v96, v43
	v_add_f32_e32 v43, v97, v43
	v_add_f32_e32 v43, v98, v43
	v_add_f32_e32 v43, v99, v43
	v_add_f32_e32 v43, v100, v43
	v_add_f32_e32 v43, v101, v43
	v_add_f32_e32 v43, v102, v43
	v_add_f32_e32 v43, v103, v43
	s_nop 1
	v_add_f32_dpp v44, v43, v43 quad_perm:[1,0,3,2] row_mask:0xf bank_mask:0xf
	v_pk_mul_f32 v[46:47], v[72:73], v[72:73]
	v_pk_mul_f32 v[48:49], v[66:67], v[66:67]
	v_pk_mul_f32 v[94:95], v[68:69], v[68:69]
	v_pk_mul_f32 v[96:97], v[62:63], v[62:63]
	s_waitcnt lgkmcnt(0)
	s_nop 1
	v_add_f32_dpp v43, v44, v44 quad_perm:[2,3,0,1] row_mask:0xf bank_mask:0xf
	s_nop 1
	v_add_f32_dpp v43, v43, v43 row_half_mirror row_mask:0xf bank_mask:0xf
	s_nop 1
	v_add_f32_dpp v43, v43, v43 row_mirror row_mask:0xf bank_mask:0xf
	s_nop 1
	v_add_f32_dpp v43, v43, v43 row_bcast:15 row_mask:0xa bank_mask:0xf
	s_nop 1
	v_add_f32_dpp v43, v43, v43 row_bcast:31 row_mask:0xc bank_mask:0xf
	s_nop 1
	v_readlane_b32 s100, v43, 63
	s_nop 1
	v_mov_b32_e32 v43, s100
	v_pk_mul_f32 v[98:99], v[64:65], v[64:65]
	v_pk_mul_f32 v[100:101], v[58:59], v[58:59]
	v_pk_mul_f32 v[102:103], v[60:61], v[60:61]
	v_fmamk_f32 v42, v42, 0x3a800000, v194
	s_waitcnt lgkmcnt(0)
	v_rsq_f32_e32 v42, v42
	s_waitcnt lgkmcnt(0)
	v_mul_f32_e32 v10, v10, v42
	v_mul_f32_e32 v14, v14, v42
	v_mul_f32_e32 v15, v15, v42
	v_mul_f32_e32 v16, v16, v42
	s_waitcnt lgkmcnt(0)
	v_mul_f32_e32 v17, v17, v42
	v_mul_f32_e32 v2, v2, v42
	v_mul_f32_e32 v6, v6, v42
	v_mul_f32_e32 v7, v7, v42
	s_waitcnt lgkmcnt(0)
	v_mul_f32_e32 v8, v8, v42
	v_mul_f32_e32 v9, v9, v42
	s_waitcnt lgkmcnt(0)
	v_pk_mul_f32 v[44:45], v[70:71], v[70:71]
	v_fmamk_f32 v43, v43, 0x3a800000, v194
	v_add_f32_e32 v44, v45, v44
	v_add_f32_e32 v44, v46, v44
	v_add_f32_e32 v44, v47, v44
	v_add_f32_e32 v44, v48, v44
	v_add_f32_e32 v44, v49, v44
	v_add_f32_e32 v44, v94, v44
	v_add_f32_e32 v44, v95, v44
	v_add_f32_e32 v44, v96, v44
	v_add_f32_e32 v44, v97, v44
	v_add_f32_e32 v44, v98, v44
	v_add_f32_e32 v44, v99, v44
	v_add_f32_e32 v44, v100, v44
	v_add_f32_e32 v44, v101, v44
	v_add_f32_e32 v44, v102, v44
	v_add_f32_e32 v44, v103, v44
	s_nop 1
	v_add_f32_dpp v45, v44, v44 quad_perm:[1,0,3,2] row_mask:0xf bank_mask:0xf
	v_pk_mul_f32 v[46:47], v[40:41], v[40:41]
	v_pk_mul_f32 v[48:49], v[34:35], v[34:35]
	v_pk_mul_f32 v[94:95], v[36:37], v[36:37]
	v_pk_mul_f32 v[96:97], v[22:23], v[22:23]
	s_waitcnt lgkmcnt(0)
	s_nop 1
	v_add_f32_dpp v44, v45, v45 quad_perm:[2,3,0,1] row_mask:0xf bank_mask:0xf
	s_nop 1
	v_add_f32_dpp v44, v44, v44 row_half_mirror row_mask:0xf bank_mask:0xf
	s_nop 1
	v_add_f32_dpp v44, v44, v44 row_mirror row_mask:0xf bank_mask:0xf
	s_nop 1
	v_add_f32_dpp v44, v44, v44 row_bcast:15 row_mask:0xa bank_mask:0xf
	s_nop 1
	v_add_f32_dpp v44, v44, v44 row_bcast:31 row_mask:0xc bank_mask:0xf
	s_nop 1
	v_readlane_b32 s100, v44, 63
	s_nop 1
	v_mov_b32_e32 v44, s100
	v_pk_mul_f32 v[98:99], v[24:25], v[24:25]
	v_pk_mul_f32 v[100:101], v[18:19], v[18:19]
	v_pk_mul_f32 v[102:103], v[20:21], v[20:21]
	v_rsq_f32_e32 v43, v43
	s_waitcnt lgkmcnt(0)
	s_waitcnt lgkmcnt(0)
	s_waitcnt lgkmcnt(0)
	s_waitcnt lgkmcnt(0)
	s_waitcnt lgkmcnt(0)
	v_fmamk_f32 v44, v44, 0x3a800000, v194
	v_rsq_f32_e32 v106, v44
	v_pk_mul_f32 v[44:45], v[38:39], v[38:39]
	s_nop 0
	v_add_f32_e32 v44, v44, v45
	v_add_f32_e32 v44, v44, v46
	v_add_f32_e32 v44, v44, v47
	v_add_f32_e32 v44, v44, v48
	v_add_f32_e32 v44, v44, v49
	v_add_f32_e32 v44, v44, v94
	v_add_f32_e32 v44, v44, v95
	v_add_f32_e32 v44, v44, v96
	v_add_f32_e32 v44, v44, v97
	v_add_f32_e32 v44, v44, v98
	v_add_f32_e32 v44, v44, v99
	v_add_f32_e32 v44, v44, v100
	v_add_f32_e32 v44, v44, v101
	v_add_f32_e32 v44, v44, v102
	v_add_f32_e32 v44, v44, v103
	s_nop 1
	v_add_f32_dpp v45, v44, v44 quad_perm:[1,0,3,2] row_mask:0xf bank_mask:0xf
	s_waitcnt lgkmcnt(0)
; #define LAS __attribute__((address_space(3)))
; #define LAS __attribute__((address_space(3)))
; __device__ __forceinline__ v4u pack8(const float (&f)[8]) { return (v4u){pk2(f[0], f[1]), pk2(f[2], f[3]), pk2(f[4], f[5]), pk2(f[6], f[7])}; }
; __device__ __forceinline__ void rowwise_phase(const Args& a, LAS unsigned char* lds, bool from_partials, bool has_y, bool has_h, bool xin_bf, int xout_mode, ...
;     ...
;                 for (int h = 0; h < 4; ++h) { float ss = 0.f;
; #pragma unroll
;                     for (int j = 0; j < 2; ++j)
; #pragma unroll
;                         for (int e = 0; e < 8; ++e) ss += v[h][j][e] * v[h][j][e];
;                     rstd[h] = __builtin_amdgcn_rsqf(wave_sum(ss) * (1.0f / DM) + EPS); }
; #pragma unroll
;                 for (int j = 0; j < 2; ++j) { const LAS float* gsp = vec + DM + 8 * lane + 512 * j; const LAS float* shp = vec + 2 * DM + 8 * lane + 512 * j;
;                     const f32x4 a0 = *(const LAS f32x4*)gsp, a1 = *(const LAS f32x4*)(gsp + 4), b0 = *(const LAS f32x4*)shp, b1 = *(const LAS f32x4*)(shp + 4);
;                     const float gs[8] = {a0.x, a0.y, a0.z, a0.w, a1.x, a1.y, a1.z, a1.w}, sh[8] = {b0.x, b0.y, b0.z, b0.w, b1.x, b1.y, b1.z, b1.w};
; #pragma unroll
;                     for (int h = 0; h < 4; ++h) { float hv[8];
; #pragma unroll
;                         for (int e = 0; e < 8; ++e) hv[e] = v[h][j][e] * rstd[h] * gs[e] + sh[e];
;                         *(v4u*)(hout + ((size_t)tile * 256 + r + h) * DM + 8 * lane + 512 * j) = pack8(hv); } }
	s_nop 1
	v_add_f32_dpp v44, v45, v45 quad_perm:[2,3,0,1] row_mask:0xf bank_mask:0xf
	s_nop 1
	v_add_f32_dpp v44, v44, v44 row_half_mirror row_mask:0xf bank_mask:0xf
	s_nop 1
	v_add_f32_dpp v44, v44, v44 row_mirror row_mask:0xf bank_mask:0xf
	s_nop 1
	v_add_f32_dpp v44, v44, v44 row_bcast:15 row_mask:0xa bank_mask:0xf
	s_nop 1
	v_add_f32_dpp v44, v44, v44 row_bcast:31 row_mask:0xc bank_mask:0xf
	s_nop 1
	v_readlane_b32 s100, v44, 63
	s_nop 1
	v_mov_b32_e32 v44, s100
	s_waitcnt lgkmcnt(0)
	s_waitcnt lgkmcnt(0)
	s_waitcnt lgkmcnt(0)
	s_waitcnt lgkmcnt(0)
	s_waitcnt lgkmcnt(0)
	v_fmamk_f32 v44, v44, 0x3a800000, v194
	v_rsq_f32_e32 v107, v44
	ds_read_b128 v[44:47], v144 offset:4096
	ds_read_b128 v[94:97], v144 offset:4112
	ds_read_b128 v[98:101], v144 offset:8192
	ds_read_b128 v[102:105], v144 offset:8208
	s_waitcnt lgkmcnt(1)
	v_fma_f32 v14, v14, v44, v98
	s_waitcnt lgkmcnt(0)
	v_fma_f32 v48, v10, v94, v102
	v_mul_f32_e32 v10, v11, v42
	v_fma_f32 v49, v10, v95, v103
	v_mul_f32_e32 v10, v12, v42
	v_fma_f32 v108, v10, v96, v104
	v_mul_f32_e32 v10, v13, v42
	v_fma_f32 v15, v15, v45, v99
	v_fma_f32 v16, v16, v46, v100
	v_fma_f32 v17, v17, v47, v101
	v_fma_f32 v13, v10, v97, v105
	v_cvt_pk_bf16_f32 v10, v14, v15
	v_cvt_pk_bf16_f32 v11, v16, v17
	v_cvt_pk_bf16_f32 v12, v48, v49
	v_add_co_u32_e32 v48, vcc, s4, v92
	v_cvt_pk_bf16_f32 v13, v108, v13
	v_mul_f32_e32 v14, v50, v43
	s_nop 0
	v_addc_co_u32_e32 v49, vcc, 0, v93, vcc
	v_add_co_u32_e32 v92, vcc, s5, v92
	v_mul_f32_e32 v15, v51, v43
	s_nop 0
	v_addc_co_u32_e32 v93, vcc, 0, v93, vcc
	global_store_dwordx4 v[92:93], v[10:13], off offset:-4096
	v_mul_f32_e32 v16, v52, v43
	v_mul_f32_e32 v17, v53, v43
	v_mul_f32_e32 v10, v54, v43
	v_mul_f32_e32 v11, v55, v43
	v_mul_f32_e32 v12, v56, v43
	v_mul_f32_e32 v13, v57, v43
	v_fma_f32 v10, v10, v44, v98
	v_fma_f32 v11, v11, v45, v99
	v_fma_f32 v12, v12, v46, v100
	v_fma_f32 v13, v13, v47, v101
	v_fma_f32 v14, v14, v94, v102
	v_fma_f32 v15, v15, v95, v103
	v_fma_f32 v16, v16, v96, v104
	v_fma_f32 v17, v17, v97, v105
	v_cvt_pk_bf16_f32 v10, v10, v11
	v_cvt_pk_bf16_f32 v11, v12, v13
	v_cvt_pk_bf16_f32 v12, v14, v15
	v_cvt_pk_bf16_f32 v13, v16, v17
	global_store_dwordx4 v[48:49], v[10:13], off offset:2048
	v_mul_f32_e32 v14, v66, v106
	v_mul_f32_e32 v15, v67, v106
	v_mul_f32_e32 v10, v70, v106
	v_mul_f32_e32 v11, v71, v106
	v_mul_f32_e32 v12, v72, v106
	v_mul_f32_e32 v13, v73, v106
	v_fma_f32 v10, v10, v44, v98
	v_fma_f32 v11, v11, v45, v99
	v_fma_f32 v12, v12, v46, v100
	v_fma_f32 v13, v13, v47, v101
	v_mul_f32_e32 v16, v68, v106
	v_mul_f32_e32 v17, v69, v106
	v_fma_f32 v14, v14, v94, v102
	v_fma_f32 v15, v15, v95, v103
	v_fma_f32 v16, v16, v96, v104
	v_fma_f32 v17, v17, v97, v105
	v_cvt_pk_bf16_f32 v10, v10, v11
	v_cvt_pk_bf16_f32 v11, v12, v13
	v_cvt_pk_bf16_f32 v12, v14, v15
	v_cvt_pk_bf16_f32 v13, v16, v17
	global_store_dwordx4 v[92:93], v[10:13], off
	v_mul_f32_e32 v14, v35, v107
	v_mul_f32_e32 v15, v36, v107
	v_mul_f32_e32 v13, v41, v107
	v_mul_f32_e32 v10, v38, v107
	v_mul_f32_e32 v11, v39, v107
	v_mul_f32_e32 v12, v40, v107
	v_fmac_f32_e32 v101, v47, v13
	v_mul_f32_e32 v13, v34, v107
	v_fma_f32 v10, v44, v10, v98
	v_fma_f32 v11, v45, v11, v99
	v_fma_f32 v12, v46, v12, v100
	v_fma_f32 v13, v94, v13, v102
	v_mul_f32_e32 v16, v37, v107
	v_fma_f32 v14, v95, v14, v103
	v_fma_f32 v15, v96, v15, v104
	v_fmac_f32_e32 v105, v97, v16
	v_cvt_pk_bf16_f32 v10, v10, v11
	v_cvt_pk_bf16_f32 v11, v12, v101
	v_cvt_pk_bf16_f32 v12, v13, v14
	v_cvt_pk_bf16_f32 v13, v15, v105
	global_store_dwordx4 v[92:93], v[10:13], off offset:2048
	ds_read_b128 v[10:13], v144 offset:6144
	ds_read_b128 v[14:17], v144 offset:6160
	ds_read_b128 v[34:37], v144 offset:10240
	ds_read_b128 v[38:41], v144 offset:10256
	s_waitcnt lgkmcnt(1)
	v_fma_f32 v6, v6, v10, v34
	s_waitcnt lgkmcnt(0)
	v_fma_f32 v44, v2, v14, v38
	v_mul_f32_e32 v2, v3, v42
	v_fma_f32 v45, v2, v15, v39
	v_mul_f32_e32 v2, v4, v42
	v_fma_f32 v46, v2, v16, v40
	v_mul_f32_e32 v2, v5, v42
	v_fma_f32 v5, v2, v17, v41
	v_fma_f32 v7, v7, v11, v35
	v_fma_f32 v8, v8, v12, v36
	v_fma_f32 v9, v9, v13, v37
	v_cvt_pk_bf16_f32 v2, v6, v7
	v_cvt_pk_bf16_f32 v3, v8, v9
	v_cvt_pk_bf16_f32 v4, v44, v45
	v_cvt_pk_bf16_f32 v5, v46, v5
	global_store_dwordx4 v[48:49], v[2:5], off offset:1024
	v_mul_f32_e32 v6, v26, v43
	v_mul_f32_e32 v7, v27, v43
	v_mul_f32_e32 v2, v30, v43
	v_mul_f32_e32 v3, v31, v43
	v_mul_f32_e32 v4, v32, v43
	v_mul_f32_e32 v5, v33, v43
	v_fma_f32 v2, v2, v10, v34
	v_fma_f32 v3, v3, v11, v35
	v_fma_f32 v4, v4, v12, v36
	v_fma_f32 v5, v5, v13, v37
	v_mul_f32_e32 v8, v28, v43
	v_mul_f32_e32 v9, v29, v43
	v_fma_f32 v6, v6, v14, v38
	v_fma_f32 v7, v7, v15, v39
	v_fma_f32 v8, v8, v16, v40
	v_fma_f32 v9, v9, v17, v41
	v_cvt_pk_bf16_f32 v2, v2, v3
	v_cvt_pk_bf16_f32 v3, v4, v5
	v_cvt_pk_bf16_f32 v4, v6, v7
	v_cvt_pk_bf16_f32 v5, v8, v9
	global_store_dwordx4 v[48:49], v[2:5], off offset:3072
	v_mul_f32_e32 v6, v58, v106
	v_mul_f32_e32 v7, v59, v106
	v_mul_f32_e32 v2, v62, v106
	v_mul_f32_e32 v3, v63, v106
	v_mul_f32_e32 v4, v64, v106
	v_mul_f32_e32 v5, v65, v106
	v_fma_f32 v2, v2, v10, v34
	v_fma_f32 v3, v3, v11, v35
	v_fma_f32 v4, v4, v12, v36
	v_fma_f32 v5, v5, v13, v37
	v_mul_f32_e32 v8, v60, v106
	v_mul_f32_e32 v9, v61, v106
	v_fma_f32 v6, v6, v14, v38
	v_fma_f32 v7, v7, v15, v39
	v_fma_f32 v8, v8, v16, v40
	v_fma_f32 v9, v9, v17, v41
	v_cvt_pk_bf16_f32 v2, v2, v3
	v_cvt_pk_bf16_f32 v3, v4, v5
	v_cvt_pk_bf16_f32 v4, v6, v7
	v_cvt_pk_bf16_f32 v5, v8, v9
	global_store_dwordx4 v[92:93], v[2:5], off offset:1024
	v_mul_f32_e32 v6, v19, v107
	v_mul_f32_e32 v7, v20, v107
	v_mul_f32_e32 v5, v25, v107
	v_mul_f32_e32 v2, v22, v107
	v_mul_f32_e32 v3, v23, v107
	v_mul_f32_e32 v4, v24, v107
	v_fmac_f32_e32 v37, v5, v13
	v_mul_f32_e32 v5, v18, v107
	v_fma_f32 v2, v2, v10, v34
	v_fma_f32 v3, v3, v11, v35
	v_fma_f32 v4, v4, v12, v36
	v_fma_f32 v5, v5, v14, v38
	v_mul_f32_e32 v8, v21, v107
	v_fma_f32 v6, v6, v15, v39
	v_fma_f32 v7, v7, v16, v40
	v_fmac_f32_e32 v41, v8, v17
	v_cvt_pk_bf16_f32 v2, v2, v3
	v_cvt_pk_bf16_f32 v3, v4, v37
	v_cvt_pk_bf16_f32 v4, v5, v6
	v_cvt_pk_bf16_f32 v5, v7, v41
	global_store_dwordx4 v[92:93], v[2:5], off offset:3072
	s_branch .LBB0_726
